# all six GEMM K-loops: LDS-DMA addresses in saddr form (scalar base + 32-bit lane offset), the per-DMA 64-bit VALU address adds removed from the load segments
# speedup vs baseline: 1.0034x; 1.0034x over previous
.LBB0_351:
	s_add_u32 s30, s28, 0xfff80080
	s_addc_u32 s31, s29, -1
	s_add_i32 s71, 0, 0x10000
	s_cmp_eq_u32 s70, 28
	s_cselect_b32 s39, s15, s31
	s_cselect_b32 s38, s62, s30
	s_cselect_b32 s31, s13, s69
	s_cselect_b32 s30, s63, s68
	s_add_i32 s74, 0, 0x14000
	v_add_u32_e32 v158, s71, v151
	v_add_u32_e32 v170, s74, v151
	ds_read_b128 v[142:145], v158
	ds_read_b128 v[146:149], v158 offset:1024
	ds_read_b128 v[154:157], v158 offset:2048
	ds_read_b128 v[158:161], v158 offset:3072
	ds_read_b128 v[162:165], v170
	ds_read_b128 v[166:169], v170 offset:1024
	ds_read_b128 v[176:179], v170 offset:2048
	ds_read_b128 v[180:183], v170 offset:3072
	s_add_i32 m0, s45, 0xc000
	ds_read_b128 v[184:187], v153
	ds_read_b128 v[188:191], v153 offset:1024
	ds_read_b128 v[192:195], v153 offset:2048
	ds_read_b128 v[196:199], v153 offset:3072
	ds_read_b128 v[208:211], v153 offset:4096
	ds_read_b128 v[222:225], v153 offset:5120
	ds_read_b128 v[226:229], v153 offset:6144
	ds_read_b128 v[230:233], v153 offset:7168
	global_load_lds_dwordx4 v140, s[28:29]
	s_add_i32 m0, s45, 0xe000
	s_nop 0
	global_load_lds_dwordx4 v138, s[28:29]
	s_waitcnt vmcnt(8)
	s_waitcnt lgkmcnt(0)
	s_barrier
	s_setprio 1
	s_waitcnt lgkmcnt(0)
	v_mfma_f32_16x16x32_bf16 v[126:129], v[142:145], v[184:187], v[126:129]
	v_mfma_f32_16x16x32_bf16 v[122:125], v[154:157], v[184:187], v[122:125]
	v_mfma_f32_16x16x32_bf16 v[110:113], v[142:145], v[192:195], v[110:113]
	v_mfma_f32_16x16x32_bf16 v[106:109], v[154:157], v[192:195], v[106:109]
	v_mfma_f32_16x16x32_bf16 v[94:97], v[142:145], v[208:211], v[94:97]
	v_mfma_f32_16x16x32_bf16 v[90:93], v[154:157], v[208:211], v[90:93]
	v_mfma_f32_16x16x32_bf16 v[78:81], v[142:145], v[226:229], v[78:81]
	v_mfma_f32_16x16x32_bf16 v[74:77], v[154:157], v[226:229], v[74:77]
	v_mfma_f32_16x16x32_bf16 v[126:129], v[146:149], v[188:191], v[126:129]
	v_mfma_f32_16x16x32_bf16 v[122:125], v[158:161], v[188:191], v[122:125]
	v_mfma_f32_16x16x32_bf16 v[110:113], v[146:149], v[196:199], v[110:113]
	v_mfma_f32_16x16x32_bf16 v[106:109], v[158:161], v[196:199], v[106:109]
	v_mfma_f32_16x16x32_bf16 v[94:97], v[146:149], v[222:225], v[94:97]
	v_mfma_f32_16x16x32_bf16 v[90:93], v[158:161], v[222:225], v[90:93]
	v_mfma_f32_16x16x32_bf16 v[78:81], v[146:149], v[230:233], v[78:81]
	v_mfma_f32_16x16x32_bf16 v[74:77], v[158:161], v[230:233], v[74:77]
	s_setprio 0
	s_setprio 1
	v_mfma_f32_16x16x32_bf16 v[118:121], v[162:165], v[184:187], v[118:121]
	v_mfma_f32_16x16x32_bf16 v[114:117], v[176:179], v[184:187], v[114:117]
	v_mfma_f32_16x16x32_bf16 v[102:105], v[162:165], v[192:195], v[102:105]
	v_mfma_f32_16x16x32_bf16 v[98:101], v[176:179], v[192:195], v[98:101]
	v_mfma_f32_16x16x32_bf16 v[86:89], v[162:165], v[208:211], v[86:89]
	v_mfma_f32_16x16x32_bf16 v[82:85], v[176:179], v[208:211], v[82:85]
	v_mfma_f32_16x16x32_bf16 v[70:73], v[162:165], v[226:229], v[70:73]
	v_mfma_f32_16x16x32_bf16 v[66:69], v[176:179], v[226:229], v[66:69]
	v_mfma_f32_16x16x32_bf16 v[118:121], v[166:169], v[188:191], v[118:121]
	v_mfma_f32_16x16x32_bf16 v[114:117], v[180:183], v[188:191], v[114:117]
	v_mfma_f32_16x16x32_bf16 v[102:105], v[166:169], v[196:199], v[102:105]
	v_mfma_f32_16x16x32_bf16 v[98:101], v[180:183], v[196:199], v[98:101]
	v_mfma_f32_16x16x32_bf16 v[86:89], v[166:169], v[222:225], v[86:89]
	v_mfma_f32_16x16x32_bf16 v[82:85], v[180:183], v[222:225], v[82:85]
	v_mfma_f32_16x16x32_bf16 v[70:73], v[166:169], v[230:233], v[70:73]
	v_mfma_f32_16x16x32_bf16 v[66:69], v[180:183], v[230:233], v[66:69]
	s_setprio 0
	s_barrier
	s_add_i32 s71, s71, s44
	s_add_u32 s98, s30, s34
	s_addc_u32 s99, s31, s35
	s_mov_b32 m0, s71
	ds_read_b128 v[184:187], v153 offset:16384
	ds_read_b128 v[188:191], v153 offset:17408
	ds_read_b128 v[192:195], v153 offset:18432
	ds_read_b128 v[196:199], v153 offset:19456
	ds_read_b128 v[208:211], v153 offset:20480
	ds_read_b128 v[222:225], v153 offset:21504
	ds_read_b128 v[226:229], v153 offset:22528
	ds_read_b128 v[230:233], v153 offset:23552
	global_load_lds_dwordx4 v130, s[30:31]
	s_add_i32 m0, s71, 0x2000
	s_add_u32 s72, s30, 0x80000
	s_addc_u32 s73, s31, 0
	s_add_i32 s71, s74, s44
	global_load_lds_dwordx4 v132, s[30:31]
	s_mov_b32 m0, s71
	s_nop 0
	global_load_lds_dwordx4 v130, s[72:73]
	s_add_i32 m0, s71, 0x2000
	s_nop 0
	global_load_lds_dwordx4 v132, s[72:73]
	s_add_u32 s100, s38, s34
	s_addc_u32 s101, s39, s35
	s_mov_b32 m0, s45
	s_nop 0
	global_load_lds_dwordx4 v136, s[38:39]
	s_mov_b32 m0, s46
	s_nop 0
	global_load_lds_dwordx4 v134, s[38:39]
	s_waitcnt vmcnt(8)
	s_waitcnt lgkmcnt(0)
	s_barrier
	s_setprio 1
	s_waitcnt lgkmcnt(0)
	v_mfma_f32_16x16x32_bf16 v[62:65], v[142:145], v[184:187], v[62:65]
	v_mfma_f32_16x16x32_bf16 v[58:61], v[154:157], v[184:187], v[58:61]
	v_mfma_f32_16x16x32_bf16 v[46:49], v[142:145], v[192:195], v[46:49]
	v_mfma_f32_16x16x32_bf16 v[42:45], v[154:157], v[192:195], v[42:45]
	v_mfma_f32_16x16x32_bf16 v[30:33], v[142:145], v[208:211], v[30:33]
	v_mfma_f32_16x16x32_bf16 v[26:29], v[154:157], v[208:211], v[26:29]
	v_mfma_f32_16x16x32_bf16 v[14:17], v[142:145], v[226:229], v[14:17]
	v_mfma_f32_16x16x32_bf16 v[10:13], v[154:157], v[226:229], v[10:13]
	v_mfma_f32_16x16x32_bf16 v[62:65], v[146:149], v[188:191], v[62:65]
	v_mfma_f32_16x16x32_bf16 v[58:61], v[158:161], v[188:191], v[58:61]
	v_mfma_f32_16x16x32_bf16 v[46:49], v[146:149], v[196:199], v[46:49]
	v_mfma_f32_16x16x32_bf16 v[42:45], v[158:161], v[196:199], v[42:45]
	v_mfma_f32_16x16x32_bf16 v[30:33], v[146:149], v[222:225], v[30:33]
	v_mfma_f32_16x16x32_bf16 v[26:29], v[158:161], v[222:225], v[26:29]
	v_mfma_f32_16x16x32_bf16 v[14:17], v[146:149], v[230:233], v[14:17]
	v_mfma_f32_16x16x32_bf16 v[10:13], v[158:161], v[230:233], v[10:13]
	s_setprio 0
	s_setprio 1
	v_mfma_f32_16x16x32_bf16 v[54:57], v[162:165], v[184:187], v[54:57]
	v_mfma_f32_16x16x32_bf16 v[50:53], v[176:179], v[184:187], v[50:53]
	v_mfma_f32_16x16x32_bf16 v[38:41], v[162:165], v[192:195], v[38:41]
	v_mfma_f32_16x16x32_bf16 v[34:37], v[176:179], v[192:195], v[34:37]
	v_mfma_f32_16x16x32_bf16 v[22:25], v[162:165], v[208:211], v[22:25]
	v_mfma_f32_16x16x32_bf16 v[18:21], v[176:179], v[208:211], v[18:21]
	v_mfma_f32_16x16x32_bf16 v[6:9], v[162:165], v[226:229], v[6:9]
	v_mfma_f32_16x16x32_bf16 v[2:5], v[176:179], v[226:229], v[2:5]
	v_mfma_f32_16x16x32_bf16 v[54:57], v[166:169], v[188:191], v[54:57]
	v_mfma_f32_16x16x32_bf16 v[50:53], v[180:183], v[188:191], v[50:53]
	v_mfma_f32_16x16x32_bf16 v[38:41], v[166:169], v[196:199], v[38:41]
	v_mfma_f32_16x16x32_bf16 v[34:37], v[180:183], v[196:199], v[34:37]
	v_mfma_f32_16x16x32_bf16 v[22:25], v[166:169], v[222:225], v[22:25]
	v_mfma_f32_16x16x32_bf16 v[18:21], v[180:183], v[222:225], v[18:21]
	v_mfma_f32_16x16x32_bf16 v[6:9], v[166:169], v[230:233], v[6:9]
	v_mfma_f32_16x16x32_bf16 v[2:5], v[180:183], v[230:233], v[2:5]
	s_setprio 0
	s_barrier
	s_add_i32 s71, 0, 0x18000
	s_add_i32 s72, 0, 0x1c000
	v_add_u32_e32 v158, s71, v151
	v_add_u32_e32 v172, s72, v151
	ds_read_b128 v[142:145], v158
	ds_read_b128 v[146:149], v158 offset:1024
	ds_read_b128 v[154:157], v158 offset:2048
	ds_read_b128 v[158:161], v158 offset:3072
	ds_read_b128 v[162:165], v172
	ds_read_b128 v[166:169], v172 offset:1024
	ds_read_b128 v[176:179], v172 offset:2048
	ds_read_b128 v[180:183], v172 offset:3072
	s_add_u32 s38, s38, 0x80000
	s_addc_u32 s39, s39, 0
	s_mov_b32 m0, s47
	ds_read_b128 v[184:187], v153 offset:32768
	ds_read_b128 v[188:191], v153 offset:33792
	ds_read_b128 v[192:195], v153 offset:34816
	ds_read_b128 v[196:199], v153 offset:35840
	ds_read_b128 v[208:211], v153 offset:36864
	ds_read_b128 v[222:225], v153 offset:37888
	ds_read_b128 v[226:229], v153 offset:38912
	ds_read_b128 v[230:233], v153 offset:39936
	global_load_lds_dwordx4 v136, s[38:39]
	s_mov_b32 m0, s48
	s_nop 0
	global_load_lds_dwordx4 v134, s[38:39]
	s_waitcnt vmcnt(8)
	s_waitcnt lgkmcnt(0)
	s_barrier
	s_setprio 1
	s_waitcnt lgkmcnt(0)
	v_mfma_f32_16x16x32_bf16 v[126:129], v[142:145], v[184:187], v[126:129]
	v_mfma_f32_16x16x32_bf16 v[122:125], v[154:157], v[184:187], v[122:125]
	v_mfma_f32_16x16x32_bf16 v[110:113], v[142:145], v[192:195], v[110:113]
	v_mfma_f32_16x16x32_bf16 v[106:109], v[154:157], v[192:195], v[106:109]
	v_mfma_f32_16x16x32_bf16 v[94:97], v[142:145], v[208:211], v[94:97]
	v_mfma_f32_16x16x32_bf16 v[90:93], v[154:157], v[208:211], v[90:93]
	v_mfma_f32_16x16x32_bf16 v[78:81], v[142:145], v[226:229], v[78:81]
	v_mfma_f32_16x16x32_bf16 v[74:77], v[154:157], v[226:229], v[74:77]
	v_mfma_f32_16x16x32_bf16 v[126:129], v[146:149], v[188:191], v[126:129]
	v_mfma_f32_16x16x32_bf16 v[122:125], v[158:161], v[188:191], v[122:125]
	v_mfma_f32_16x16x32_bf16 v[110:113], v[146:149], v[196:199], v[110:113]
	v_mfma_f32_16x16x32_bf16 v[106:109], v[158:161], v[196:199], v[106:109]
	v_mfma_f32_16x16x32_bf16 v[94:97], v[146:149], v[222:225], v[94:97]
	v_mfma_f32_16x16x32_bf16 v[90:93], v[158:161], v[222:225], v[90:93]
	v_mfma_f32_16x16x32_bf16 v[78:81], v[146:149], v[230:233], v[78:81]
	v_mfma_f32_16x16x32_bf16 v[74:77], v[158:161], v[230:233], v[74:77]
	s_setprio 0
	s_setprio 1
	v_mfma_f32_16x16x32_bf16 v[118:121], v[162:165], v[184:187], v[118:121]
	v_mfma_f32_16x16x32_bf16 v[114:117], v[176:179], v[184:187], v[114:117]
	v_mfma_f32_16x16x32_bf16 v[102:105], v[162:165], v[192:195], v[102:105]
	v_mfma_f32_16x16x32_bf16 v[98:101], v[176:179], v[192:195], v[98:101]
	v_mfma_f32_16x16x32_bf16 v[86:89], v[162:165], v[208:211], v[86:89]
	v_mfma_f32_16x16x32_bf16 v[82:85], v[176:179], v[208:211], v[82:85]
	v_mfma_f32_16x16x32_bf16 v[70:73], v[162:165], v[226:229], v[70:73]
	v_mfma_f32_16x16x32_bf16 v[66:69], v[176:179], v[226:229], v[66:69]
	v_mfma_f32_16x16x32_bf16 v[118:121], v[166:169], v[188:191], v[118:121]
	v_mfma_f32_16x16x32_bf16 v[114:117], v[180:183], v[188:191], v[114:117]
	v_mfma_f32_16x16x32_bf16 v[102:105], v[166:169], v[196:199], v[102:105]
	v_mfma_f32_16x16x32_bf16 v[98:101], v[180:183], v[196:199], v[98:101]
	v_mfma_f32_16x16x32_bf16 v[86:89], v[166:169], v[222:225], v[86:89]
	v_mfma_f32_16x16x32_bf16 v[82:85], v[180:183], v[222:225], v[82:85]
	v_mfma_f32_16x16x32_bf16 v[70:73], v[166:169], v[230:233], v[70:73]
	v_mfma_f32_16x16x32_bf16 v[66:69], v[180:183], v[230:233], v[66:69]
	s_setprio 0
	s_barrier
	s_add_i32 s38, s71, s44
	s_mov_b32 m0, s38
	ds_read_b128 v[184:187], v153 offset:49152
	ds_read_b128 v[188:191], v153 offset:50176
	ds_read_b128 v[192:195], v153 offset:51200
	ds_read_b128 v[196:199], v153 offset:52224
	ds_read_b128 v[208:211], v153 offset:53248
	ds_read_b128 v[222:225], v153 offset:54272
	ds_read_b128 v[226:229], v153 offset:55296
	ds_read_b128 v[230:233], v153 offset:56320
	global_load_lds_dwordx4 v130, s[98:99]
	s_add_i32 m0, s38, 0x2000
	s_add_u32 s30, s30, 0x80080
	s_addc_u32 s31, s31, 0
	s_add_i32 s38, s72, s44
	global_load_lds_dwordx4 v132, s[98:99]
	s_mov_b32 m0, s38
	s_nop 0
	global_load_lds_dwordx4 v130, s[30:31]
	s_add_i32 m0, s38, 0x2000
	s_nop 0
	global_load_lds_dwordx4 v132, s[30:31]
	s_mov_b32 m0, s57
	s_nop 0
	global_load_lds_dwordx4 v136, s[100:101]
	s_mov_b32 m0, s58
	s_nop 0
	global_load_lds_dwordx4 v134, s[100:101]
	s_waitcnt vmcnt(8)
	s_waitcnt lgkmcnt(0)
	s_barrier
	s_setprio 1
	s_waitcnt lgkmcnt(0)
	v_mfma_f32_16x16x32_bf16 v[62:65], v[142:145], v[184:187], v[62:65]
	v_mfma_f32_16x16x32_bf16 v[58:61], v[154:157], v[184:187], v[58:61]
	v_mfma_f32_16x16x32_bf16 v[46:49], v[142:145], v[192:195], v[46:49]
	v_mfma_f32_16x16x32_bf16 v[42:45], v[154:157], v[192:195], v[42:45]
	v_mfma_f32_16x16x32_bf16 v[30:33], v[142:145], v[208:211], v[30:33]
	v_mfma_f32_16x16x32_bf16 v[26:29], v[154:157], v[208:211], v[26:29]
	v_mfma_f32_16x16x32_bf16 v[14:17], v[142:145], v[226:229], v[14:17]
	v_mfma_f32_16x16x32_bf16 v[10:13], v[154:157], v[226:229], v[10:13]
	v_mfma_f32_16x16x32_bf16 v[62:65], v[146:149], v[188:191], v[62:65]
	v_mfma_f32_16x16x32_bf16 v[58:61], v[158:161], v[188:191], v[58:61]
	v_mfma_f32_16x16x32_bf16 v[46:49], v[146:149], v[196:199], v[46:49]
	v_mfma_f32_16x16x32_bf16 v[42:45], v[158:161], v[196:199], v[42:45]
	v_mfma_f32_16x16x32_bf16 v[30:33], v[146:149], v[222:225], v[30:33]
	v_mfma_f32_16x16x32_bf16 v[26:29], v[158:161], v[222:225], v[26:29]
	v_mfma_f32_16x16x32_bf16 v[14:17], v[146:149], v[230:233], v[14:17]
	v_mfma_f32_16x16x32_bf16 v[10:13], v[158:161], v[230:233], v[10:13]
	s_setprio 0
	s_setprio 1
	v_mfma_f32_16x16x32_bf16 v[54:57], v[162:165], v[184:187], v[54:57]
	v_mfma_f32_16x16x32_bf16 v[50:53], v[176:179], v[184:187], v[50:53]
	v_mfma_f32_16x16x32_bf16 v[38:41], v[162:165], v[192:195], v[38:41]
	v_mfma_f32_16x16x32_bf16 v[34:37], v[176:179], v[192:195], v[34:37]
	v_mfma_f32_16x16x32_bf16 v[22:25], v[162:165], v[208:211], v[22:25]
	v_mfma_f32_16x16x32_bf16 v[18:21], v[176:179], v[208:211], v[18:21]
	v_mfma_f32_16x16x32_bf16 v[6:9], v[162:165], v[226:229], v[6:9]
	v_mfma_f32_16x16x32_bf16 v[2:5], v[176:179], v[226:229], v[2:5]
	v_mfma_f32_16x16x32_bf16 v[54:57], v[166:169], v[188:191], v[54:57]
	v_mfma_f32_16x16x32_bf16 v[50:53], v[180:183], v[188:191], v[50:53]
	v_mfma_f32_16x16x32_bf16 v[38:41], v[166:169], v[196:199], v[38:41]
	v_mfma_f32_16x16x32_bf16 v[34:37], v[180:183], v[196:199], v[34:37]
	v_mfma_f32_16x16x32_bf16 v[22:25], v[166:169], v[222:225], v[22:25]
	v_mfma_f32_16x16x32_bf16 v[18:21], v[180:183], v[222:225], v[18:21]
	v_mfma_f32_16x16x32_bf16 v[6:9], v[166:169], v[230:233], v[6:9]
	v_mfma_f32_16x16x32_bf16 v[2:5], v[180:183], v[230:233], v[2:5]
	s_setprio 0
	s_barrier
	s_add_i32 s70, s70, 2
	s_add_u32 s68, s68, 0x100
	s_addc_u32 s69, s69, 0
	s_add_u32 s28, s28, 0x100
	s_addc_u32 s29, s29, 0
	s_cmp_gt_u32 s70, 29
	s_cbranch_scc0 .LBB0_351
	s_and_b64 vcc, exec, s[10:11]
	s_cbranch_vccz .LBB0_354
	s_barrier

.LBB0_663:
	s_add_u32 s24, s16, 0xfff80080
	s_addc_u32 s25, s17, -1
	s_add_i32 s58, 0, 0x10000
	s_cmp_eq_u32 s57, 28
	s_cselect_b32 s29, s11, s25
	s_cselect_b32 s28, s49, s24
	s_cselect_b32 s25, s9, s56
	s_cselect_b32 s24, s54, s55
	s_add_i32 s60, 0, 0x14000
	v_add_u32_e32 v158, s58, v147
	v_add_u32_e32 v170, s60, v147
	ds_read_b128 v[142:145], v158
	ds_read_b128 v[150:153], v158 offset:1024
	ds_read_b128 v[154:157], v158 offset:2048
	ds_read_b128 v[158:161], v158 offset:3072
	ds_read_b128 v[162:165], v170
	ds_read_b128 v[166:169], v170 offset:1024
	ds_read_b128 v[176:179], v170 offset:2048
	ds_read_b128 v[180:183], v170 offset:3072
	s_add_i32 m0, s38, 0xc000
	ds_read_b128 v[184:187], v149
	ds_read_b128 v[188:191], v149 offset:1024
	ds_read_b128 v[192:195], v149 offset:2048
	ds_read_b128 v[196:199], v149 offset:3072
	ds_read_b128 v[208:211], v149 offset:4096
	ds_read_b128 v[222:225], v149 offset:5120
	ds_read_b128 v[226:229], v149 offset:6144
	ds_read_b128 v[230:233], v149 offset:7168
	global_load_lds_dwordx4 v140, s[16:17]
	s_add_i32 m0, s38, 0xe000
	s_nop 0
	global_load_lds_dwordx4 v138, s[16:17]
	s_waitcnt vmcnt(8)
	s_waitcnt lgkmcnt(0)
	s_barrier
	s_setprio 1
	s_waitcnt lgkmcnt(0)
	v_mfma_f32_16x16x32_bf16 v[126:129], v[142:145], v[184:187], v[126:129]
	v_mfma_f32_16x16x32_bf16 v[122:125], v[154:157], v[184:187], v[122:125]
	v_mfma_f32_16x16x32_bf16 v[118:121], v[142:145], v[192:195], v[118:121]
	v_mfma_f32_16x16x32_bf16 v[110:113], v[154:157], v[192:195], v[110:113]
	v_mfma_f32_16x16x32_bf16 v[102:105], v[142:145], v[208:211], v[102:105]
	v_mfma_f32_16x16x32_bf16 v[94:97], v[154:157], v[208:211], v[94:97]
	v_mfma_f32_16x16x32_bf16 v[86:89], v[142:145], v[226:229], v[86:89]
	v_mfma_f32_16x16x32_bf16 v[78:81], v[154:157], v[226:229], v[78:81]
	v_mfma_f32_16x16x32_bf16 v[126:129], v[150:153], v[188:191], v[126:129]
	v_mfma_f32_16x16x32_bf16 v[122:125], v[158:161], v[188:191], v[122:125]
	v_mfma_f32_16x16x32_bf16 v[118:121], v[150:153], v[196:199], v[118:121]
	v_mfma_f32_16x16x32_bf16 v[110:113], v[158:161], v[196:199], v[110:113]
	v_mfma_f32_16x16x32_bf16 v[102:105], v[150:153], v[222:225], v[102:105]
	v_mfma_f32_16x16x32_bf16 v[94:97], v[158:161], v[222:225], v[94:97]
	v_mfma_f32_16x16x32_bf16 v[86:89], v[150:153], v[230:233], v[86:89]
	v_mfma_f32_16x16x32_bf16 v[78:81], v[158:161], v[230:233], v[78:81]
	s_setprio 0
	s_setprio 1
	v_mfma_f32_16x16x32_bf16 v[114:117], v[162:165], v[184:187], v[114:117]
	v_mfma_f32_16x16x32_bf16 v[106:109], v[176:179], v[184:187], v[106:109]
	v_mfma_f32_16x16x32_bf16 v[98:101], v[162:165], v[192:195], v[98:101]
	v_mfma_f32_16x16x32_bf16 v[90:93], v[176:179], v[192:195], v[90:93]
	v_mfma_f32_16x16x32_bf16 v[82:85], v[162:165], v[208:211], v[82:85]
	v_mfma_f32_16x16x32_bf16 v[74:77], v[176:179], v[208:211], v[74:77]
	v_mfma_f32_16x16x32_bf16 v[70:73], v[162:165], v[226:229], v[70:73]
	v_mfma_f32_16x16x32_bf16 v[66:69], v[176:179], v[226:229], v[66:69]
	v_mfma_f32_16x16x32_bf16 v[114:117], v[166:169], v[188:191], v[114:117]
	v_mfma_f32_16x16x32_bf16 v[106:109], v[180:183], v[188:191], v[106:109]
	v_mfma_f32_16x16x32_bf16 v[98:101], v[166:169], v[196:199], v[98:101]
	v_mfma_f32_16x16x32_bf16 v[90:93], v[180:183], v[196:199], v[90:93]
	v_mfma_f32_16x16x32_bf16 v[82:85], v[166:169], v[222:225], v[82:85]
	v_mfma_f32_16x16x32_bf16 v[74:77], v[180:183], v[222:225], v[74:77]
	v_mfma_f32_16x16x32_bf16 v[70:73], v[166:169], v[230:233], v[70:73]
	v_mfma_f32_16x16x32_bf16 v[66:69], v[180:183], v[230:233], v[66:69]
	s_setprio 0
	s_barrier
	s_add_i32 s58, s58, s37
	s_add_u32 s98, s24, s34
	s_addc_u32 s99, s25, s35
	s_mov_b32 m0, s58
	ds_read_b128 v[184:187], v149 offset:16384
	ds_read_b128 v[188:191], v149 offset:17408
	ds_read_b128 v[192:195], v149 offset:18432
	ds_read_b128 v[196:199], v149 offset:19456
	ds_read_b128 v[208:211], v149 offset:20480
	ds_read_b128 v[222:225], v149 offset:21504
	ds_read_b128 v[226:229], v149 offset:22528
	ds_read_b128 v[230:233], v149 offset:23552
	global_load_lds_dwordx4 v130, s[24:25]
	s_add_i32 m0, s58, 0x2000
	s_add_u32 s58, s24, 0x80000
	s_addc_u32 s59, s25, 0
	s_add_i32 s60, s60, s37
	global_load_lds_dwordx4 v132, s[24:25]
	s_mov_b32 m0, s60
	s_nop 0
	global_load_lds_dwordx4 v130, s[58:59]
	s_add_i32 m0, s60, 0x2000
	s_nop 0
	global_load_lds_dwordx4 v132, s[58:59]
	s_add_u32 s100, s28, s34
	s_addc_u32 s101, s29, s35
	s_mov_b32 m0, s38
	s_nop 0
	global_load_lds_dwordx4 v136, s[28:29]
	s_mov_b32 m0, s39
	s_nop 0
	global_load_lds_dwordx4 v134, s[28:29]
	s_waitcnt vmcnt(8)
	s_waitcnt lgkmcnt(0)
	s_barrier
	s_setprio 1
	s_waitcnt lgkmcnt(0)
	v_mfma_f32_16x16x32_bf16 v[62:65], v[142:145], v[184:187], v[62:65]
	v_mfma_f32_16x16x32_bf16 v[58:61], v[154:157], v[184:187], v[58:61]
	v_mfma_f32_16x16x32_bf16 v[54:57], v[142:145], v[192:195], v[54:57]
	v_mfma_f32_16x16x32_bf16 v[46:49], v[154:157], v[192:195], v[46:49]
	v_mfma_f32_16x16x32_bf16 v[38:41], v[142:145], v[208:211], v[38:41]
	v_mfma_f32_16x16x32_bf16 v[30:33], v[154:157], v[208:211], v[30:33]
	v_mfma_f32_16x16x32_bf16 v[22:25], v[142:145], v[226:229], v[22:25]
	v_mfma_f32_16x16x32_bf16 v[14:17], v[154:157], v[226:229], v[14:17]
	v_mfma_f32_16x16x32_bf16 v[62:65], v[150:153], v[188:191], v[62:65]
	v_mfma_f32_16x16x32_bf16 v[58:61], v[158:161], v[188:191], v[58:61]
	v_mfma_f32_16x16x32_bf16 v[54:57], v[150:153], v[196:199], v[54:57]
	v_mfma_f32_16x16x32_bf16 v[46:49], v[158:161], v[196:199], v[46:49]
	v_mfma_f32_16x16x32_bf16 v[38:41], v[150:153], v[222:225], v[38:41]
	v_mfma_f32_16x16x32_bf16 v[30:33], v[158:161], v[222:225], v[30:33]
	v_mfma_f32_16x16x32_bf16 v[22:25], v[150:153], v[230:233], v[22:25]
	v_mfma_f32_16x16x32_bf16 v[14:17], v[158:161], v[230:233], v[14:17]
	s_setprio 0
	s_setprio 1
	v_mfma_f32_16x16x32_bf16 v[50:53], v[162:165], v[184:187], v[50:53]
	v_mfma_f32_16x16x32_bf16 v[42:45], v[176:179], v[184:187], v[42:45]
	v_mfma_f32_16x16x32_bf16 v[34:37], v[162:165], v[192:195], v[34:37]
	v_mfma_f32_16x16x32_bf16 v[26:29], v[176:179], v[192:195], v[26:29]
	v_mfma_f32_16x16x32_bf16 v[18:21], v[162:165], v[208:211], v[18:21]
	v_mfma_f32_16x16x32_bf16 v[10:13], v[176:179], v[208:211], v[10:13]
	v_mfma_f32_16x16x32_bf16 v[6:9], v[162:165], v[226:229], v[6:9]
	v_mfma_f32_16x16x32_bf16 v[2:5], v[176:179], v[226:229], v[2:5]
	v_mfma_f32_16x16x32_bf16 v[50:53], v[166:169], v[188:191], v[50:53]
	v_mfma_f32_16x16x32_bf16 v[42:45], v[180:183], v[188:191], v[42:45]
	v_mfma_f32_16x16x32_bf16 v[34:37], v[166:169], v[196:199], v[34:37]
	v_mfma_f32_16x16x32_bf16 v[26:29], v[180:183], v[196:199], v[26:29]
	v_mfma_f32_16x16x32_bf16 v[18:21], v[166:169], v[222:225], v[18:21]
	v_mfma_f32_16x16x32_bf16 v[10:13], v[180:183], v[222:225], v[10:13]
	v_mfma_f32_16x16x32_bf16 v[6:9], v[166:169], v[230:233], v[6:9]
	v_mfma_f32_16x16x32_bf16 v[2:5], v[180:183], v[230:233], v[2:5]
	s_setprio 0
	s_barrier
	s_add_i32 s58, 0, 0x18000
	s_add_i32 s59, 0, 0x1c000
	v_add_u32_e32 v158, s58, v147
	v_add_u32_e32 v172, s59, v147
	ds_read_b128 v[142:145], v158
	ds_read_b128 v[150:153], v158 offset:1024
	ds_read_b128 v[154:157], v158 offset:2048
	ds_read_b128 v[158:161], v158 offset:3072
	ds_read_b128 v[162:165], v172
	ds_read_b128 v[166:169], v172 offset:1024
	ds_read_b128 v[176:179], v172 offset:2048
	ds_read_b128 v[180:183], v172 offset:3072
	s_add_u32 s28, s28, 0x80000
	s_addc_u32 s29, s29, 0
	s_mov_b32 m0, s40
	ds_read_b128 v[184:187], v149 offset:32768
	ds_read_b128 v[188:191], v149 offset:33792
	ds_read_b128 v[192:195], v149 offset:34816
	ds_read_b128 v[196:199], v149 offset:35840
	ds_read_b128 v[208:211], v149 offset:36864
	ds_read_b128 v[222:225], v149 offset:37888
	ds_read_b128 v[226:229], v149 offset:38912
	ds_read_b128 v[230:233], v149 offset:39936
	global_load_lds_dwordx4 v136, s[28:29]
	s_mov_b32 m0, s41
	s_nop 0
	global_load_lds_dwordx4 v134, s[28:29]
	s_waitcnt vmcnt(8)
	s_waitcnt lgkmcnt(0)
	s_barrier
	s_setprio 1
	s_waitcnt lgkmcnt(0)
	v_mfma_f32_16x16x32_bf16 v[126:129], v[142:145], v[184:187], v[126:129]
	v_mfma_f32_16x16x32_bf16 v[122:125], v[154:157], v[184:187], v[122:125]
	v_mfma_f32_16x16x32_bf16 v[118:121], v[142:145], v[192:195], v[118:121]
	v_mfma_f32_16x16x32_bf16 v[110:113], v[154:157], v[192:195], v[110:113]
	v_mfma_f32_16x16x32_bf16 v[102:105], v[142:145], v[208:211], v[102:105]
	v_mfma_f32_16x16x32_bf16 v[94:97], v[154:157], v[208:211], v[94:97]
	v_mfma_f32_16x16x32_bf16 v[86:89], v[142:145], v[226:229], v[86:89]
	v_mfma_f32_16x16x32_bf16 v[78:81], v[154:157], v[226:229], v[78:81]
	v_mfma_f32_16x16x32_bf16 v[126:129], v[150:153], v[188:191], v[126:129]
	v_mfma_f32_16x16x32_bf16 v[122:125], v[158:161], v[188:191], v[122:125]
	v_mfma_f32_16x16x32_bf16 v[118:121], v[150:153], v[196:199], v[118:121]
	v_mfma_f32_16x16x32_bf16 v[110:113], v[158:161], v[196:199], v[110:113]
	v_mfma_f32_16x16x32_bf16 v[102:105], v[150:153], v[222:225], v[102:105]
	v_mfma_f32_16x16x32_bf16 v[94:97], v[158:161], v[222:225], v[94:97]
	v_mfma_f32_16x16x32_bf16 v[86:89], v[150:153], v[230:233], v[86:89]
	v_mfma_f32_16x16x32_bf16 v[78:81], v[158:161], v[230:233], v[78:81]
	s_setprio 0
	s_setprio 1
	v_mfma_f32_16x16x32_bf16 v[114:117], v[162:165], v[184:187], v[114:117]
	v_mfma_f32_16x16x32_bf16 v[106:109], v[176:179], v[184:187], v[106:109]
	v_mfma_f32_16x16x32_bf16 v[98:101], v[162:165], v[192:195], v[98:101]
	v_mfma_f32_16x16x32_bf16 v[90:93], v[176:179], v[192:195], v[90:93]
	v_mfma_f32_16x16x32_bf16 v[82:85], v[162:165], v[208:211], v[82:85]
	v_mfma_f32_16x16x32_bf16 v[74:77], v[176:179], v[208:211], v[74:77]
	v_mfma_f32_16x16x32_bf16 v[70:73], v[162:165], v[226:229], v[70:73]
	v_mfma_f32_16x16x32_bf16 v[66:69], v[176:179], v[226:229], v[66:69]
	v_mfma_f32_16x16x32_bf16 v[114:117], v[166:169], v[188:191], v[114:117]
	v_mfma_f32_16x16x32_bf16 v[106:109], v[180:183], v[188:191], v[106:109]
	v_mfma_f32_16x16x32_bf16 v[98:101], v[166:169], v[196:199], v[98:101]
	v_mfma_f32_16x16x32_bf16 v[90:93], v[180:183], v[196:199], v[90:93]
	v_mfma_f32_16x16x32_bf16 v[82:85], v[166:169], v[222:225], v[82:85]
	v_mfma_f32_16x16x32_bf16 v[74:77], v[180:183], v[222:225], v[74:77]
	v_mfma_f32_16x16x32_bf16 v[70:73], v[166:169], v[230:233], v[70:73]
	v_mfma_f32_16x16x32_bf16 v[66:69], v[180:183], v[230:233], v[66:69]
	s_setprio 0
	s_barrier
	s_add_i32 s28, s58, s37
	s_mov_b32 m0, s28
	ds_read_b128 v[184:187], v149 offset:49152
	ds_read_b128 v[188:191], v149 offset:50176
	ds_read_b128 v[192:195], v149 offset:51200
	ds_read_b128 v[196:199], v149 offset:52224
	ds_read_b128 v[208:211], v149 offset:53248
	ds_read_b128 v[222:225], v149 offset:54272
	ds_read_b128 v[226:229], v149 offset:55296
	ds_read_b128 v[230:233], v149 offset:56320
	global_load_lds_dwordx4 v130, s[98:99]
	s_add_i32 m0, s28, 0x2000
	s_add_u32 s24, s24, 0x80080
	s_addc_u32 s25, s25, 0
	s_add_i32 s28, s59, s37
	global_load_lds_dwordx4 v132, s[98:99]
	s_mov_b32 m0, s28
	s_nop 0
	global_load_lds_dwordx4 v130, s[24:25]
	s_add_i32 m0, s28, 0x2000
	s_nop 0
	global_load_lds_dwordx4 v132, s[24:25]
	s_mov_b32 m0, s44
	s_nop 0
	global_load_lds_dwordx4 v136, s[100:101]
	s_mov_b32 m0, s45
	s_nop 0
	global_load_lds_dwordx4 v134, s[100:101]
	s_waitcnt vmcnt(8)
	s_waitcnt lgkmcnt(0)
	s_barrier
	s_setprio 1
	s_waitcnt lgkmcnt(0)
	v_mfma_f32_16x16x32_bf16 v[62:65], v[142:145], v[184:187], v[62:65]
	v_mfma_f32_16x16x32_bf16 v[58:61], v[154:157], v[184:187], v[58:61]
	v_mfma_f32_16x16x32_bf16 v[54:57], v[142:145], v[192:195], v[54:57]
	v_mfma_f32_16x16x32_bf16 v[46:49], v[154:157], v[192:195], v[46:49]
	v_mfma_f32_16x16x32_bf16 v[38:41], v[142:145], v[208:211], v[38:41]
	v_mfma_f32_16x16x32_bf16 v[30:33], v[154:157], v[208:211], v[30:33]
	v_mfma_f32_16x16x32_bf16 v[22:25], v[142:145], v[226:229], v[22:25]
	v_mfma_f32_16x16x32_bf16 v[14:17], v[154:157], v[226:229], v[14:17]
	v_mfma_f32_16x16x32_bf16 v[62:65], v[150:153], v[188:191], v[62:65]
	v_mfma_f32_16x16x32_bf16 v[58:61], v[158:161], v[188:191], v[58:61]
	v_mfma_f32_16x16x32_bf16 v[54:57], v[150:153], v[196:199], v[54:57]
	v_mfma_f32_16x16x32_bf16 v[46:49], v[158:161], v[196:199], v[46:49]
	v_mfma_f32_16x16x32_bf16 v[38:41], v[150:153], v[222:225], v[38:41]
	v_mfma_f32_16x16x32_bf16 v[30:33], v[158:161], v[222:225], v[30:33]
	v_mfma_f32_16x16x32_bf16 v[22:25], v[150:153], v[230:233], v[22:25]
	v_mfma_f32_16x16x32_bf16 v[14:17], v[158:161], v[230:233], v[14:17]
	s_setprio 0
	s_setprio 1
	v_mfma_f32_16x16x32_bf16 v[50:53], v[162:165], v[184:187], v[50:53]
	v_mfma_f32_16x16x32_bf16 v[42:45], v[176:179], v[184:187], v[42:45]
	v_mfma_f32_16x16x32_bf16 v[34:37], v[162:165], v[192:195], v[34:37]
	v_mfma_f32_16x16x32_bf16 v[26:29], v[176:179], v[192:195], v[26:29]
	v_mfma_f32_16x16x32_bf16 v[18:21], v[162:165], v[208:211], v[18:21]
	v_mfma_f32_16x16x32_bf16 v[10:13], v[176:179], v[208:211], v[10:13]
	v_mfma_f32_16x16x32_bf16 v[6:9], v[162:165], v[226:229], v[6:9]
	v_mfma_f32_16x16x32_bf16 v[2:5], v[176:179], v[226:229], v[2:5]
	v_mfma_f32_16x16x32_bf16 v[50:53], v[166:169], v[188:191], v[50:53]
	v_mfma_f32_16x16x32_bf16 v[42:45], v[180:183], v[188:191], v[42:45]
	v_mfma_f32_16x16x32_bf16 v[34:37], v[166:169], v[196:199], v[34:37]
	v_mfma_f32_16x16x32_bf16 v[26:29], v[180:183], v[196:199], v[26:29]
	v_mfma_f32_16x16x32_bf16 v[18:21], v[166:169], v[222:225], v[18:21]
	v_mfma_f32_16x16x32_bf16 v[10:13], v[180:183], v[222:225], v[10:13]
	v_mfma_f32_16x16x32_bf16 v[6:9], v[166:169], v[230:233], v[6:9]
	v_mfma_f32_16x16x32_bf16 v[2:5], v[180:183], v[230:233], v[2:5]
	s_setprio 0
	s_barrier
	s_add_i32 s57, s57, 2
	s_add_u32 s55, s55, 0x100
	s_addc_u32 s56, s56, 0
	s_add_u32 s16, s16, 0x100
	s_addc_u32 s17, s17, 0
	s_cmp_gt_u32 s57, 29
	s_cbranch_scc0 .LBB0_663
	s_and_b64 vcc, exec, s[6:7]
	s_cbranch_vccz .LBB0_666
	s_barrier

.LBB0_1029:
	s_add_u32 s28, s24, 0xfff80080
	s_addc_u32 s29, s25, -1
	s_add_i32 s68, 0, 0x10000
	s_cmp_eq_u32 s63, 28
	s_cselect_b32 s31, s13, s29
	s_cselect_b32 s30, s59, s28
	s_cselect_b32 s29, s11, s62
	s_cselect_b32 s28, s60, s61
	s_add_i32 s70, 0, 0x14000
	v_add_u32_e32 v118, s68, v195
	v_add_u32_e32 v160, s70, v195
	ds_read_b128 v[106:109], v118
	ds_read_b128 v[110:113], v118 offset:1024
	ds_read_b128 v[114:117], v118 offset:2048
	ds_read_b128 v[118:121], v118 offset:3072
	ds_read_b128 v[148:151], v160
	ds_read_b128 v[152:155], v160 offset:1024
	ds_read_b128 v[156:159], v160 offset:2048
	ds_read_b128 v[160:163], v160 offset:3072
	s_add_i32 m0, s45, 0xc000
	ds_read_b128 v[164:167], v197
	ds_read_b128 v[182:185], v197 offset:1024
	ds_read_b128 v[186:189], v197 offset:2048
	ds_read_b128 v[190:193], v197 offset:3072
	ds_read_b128 v[208:211], v197 offset:4096
	ds_read_b128 v[222:225], v197 offset:5120
	ds_read_b128 v[226:229], v197 offset:6144
	ds_read_b128 v[230:233], v197 offset:7168
	global_load_lds_dwordx4 v180, s[24:25]
	s_add_i32 m0, s45, 0xe000
	s_nop 0
	global_load_lds_dwordx4 v178, s[24:25]
	s_waitcnt vmcnt(8)
	s_waitcnt lgkmcnt(0)
	s_barrier
	s_setprio 1
	s_waitcnt lgkmcnt(0)
	v_mfma_f32_16x16x32_bf16 v[144:147], v[106:109], v[164:167], v[144:147]
	v_mfma_f32_16x16x32_bf16 v[140:143], v[114:117], v[164:167], v[140:143]
	v_mfma_f32_16x16x32_bf16 v[136:139], v[106:109], v[186:189], v[136:139]
	v_mfma_f32_16x16x32_bf16 v[132:135], v[114:117], v[186:189], v[132:135]
	v_mfma_f32_16x16x32_bf16 v[94:97], v[106:109], v[208:211], v[94:97]
	v_mfma_f32_16x16x32_bf16 v[90:93], v[114:117], v[208:211], v[90:93]
	v_mfma_f32_16x16x32_bf16 v[78:81], v[106:109], v[226:229], v[78:81]
	v_mfma_f32_16x16x32_bf16 v[74:77], v[114:117], v[226:229], v[74:77]
	v_mfma_f32_16x16x32_bf16 v[144:147], v[110:113], v[182:185], v[144:147]
	v_mfma_f32_16x16x32_bf16 v[140:143], v[118:121], v[182:185], v[140:143]
	v_mfma_f32_16x16x32_bf16 v[136:139], v[110:113], v[190:193], v[136:139]
	v_mfma_f32_16x16x32_bf16 v[132:135], v[118:121], v[190:193], v[132:135]
	v_mfma_f32_16x16x32_bf16 v[94:97], v[110:113], v[222:225], v[94:97]
	v_mfma_f32_16x16x32_bf16 v[90:93], v[118:121], v[222:225], v[90:93]
	v_mfma_f32_16x16x32_bf16 v[78:81], v[110:113], v[230:233], v[78:81]
	v_mfma_f32_16x16x32_bf16 v[74:77], v[118:121], v[230:233], v[74:77]
	s_setprio 0
	s_setprio 1
	v_mfma_f32_16x16x32_bf16 v[126:129], v[148:151], v[164:167], v[126:129]
	v_mfma_f32_16x16x32_bf16 v[122:125], v[156:159], v[164:167], v[122:125]
	v_mfma_f32_16x16x32_bf16 v[102:105], v[148:151], v[186:189], v[102:105]
	v_mfma_f32_16x16x32_bf16 v[98:101], v[156:159], v[186:189], v[98:101]
	v_mfma_f32_16x16x32_bf16 v[86:89], v[148:151], v[208:211], v[86:89]
	v_mfma_f32_16x16x32_bf16 v[82:85], v[156:159], v[208:211], v[82:85]
	v_mfma_f32_16x16x32_bf16 v[70:73], v[148:151], v[226:229], v[70:73]
	v_mfma_f32_16x16x32_bf16 v[66:69], v[156:159], v[226:229], v[66:69]
	v_mfma_f32_16x16x32_bf16 v[126:129], v[152:155], v[182:185], v[126:129]
	v_mfma_f32_16x16x32_bf16 v[122:125], v[160:163], v[182:185], v[122:125]
	v_mfma_f32_16x16x32_bf16 v[102:105], v[152:155], v[190:193], v[102:105]
	v_mfma_f32_16x16x32_bf16 v[98:101], v[160:163], v[190:193], v[98:101]
	v_mfma_f32_16x16x32_bf16 v[86:89], v[152:155], v[222:225], v[86:89]
	v_mfma_f32_16x16x32_bf16 v[82:85], v[160:163], v[222:225], v[82:85]
	v_mfma_f32_16x16x32_bf16 v[70:73], v[152:155], v[230:233], v[70:73]
	v_mfma_f32_16x16x32_bf16 v[66:69], v[160:163], v[230:233], v[66:69]
	s_setprio 0
	s_barrier
	s_add_i32 s68, s68, s44
	s_add_u32 s98, s28, s34
	s_addc_u32 s99, s29, s35
	s_mov_b32 m0, s68
	ds_read_b128 v[164:167], v197 offset:16384
	ds_read_b128 v[182:185], v197 offset:17408
	ds_read_b128 v[186:189], v197 offset:18432
	ds_read_b128 v[190:193], v197 offset:19456
	ds_read_b128 v[208:211], v197 offset:20480
	ds_read_b128 v[222:225], v197 offset:21504
	ds_read_b128 v[226:229], v197 offset:22528
	ds_read_b128 v[230:233], v197 offset:23552
	global_load_lds_dwordx4 v130, s[28:29]
	s_add_i32 m0, s68, 0x2000
	s_add_u32 s68, s28, 0x80000
	s_addc_u32 s69, s29, 0
	s_add_i32 s70, s70, s44
	global_load_lds_dwordx4 v168, s[28:29]
	s_mov_b32 m0, s70
	s_nop 0
	global_load_lds_dwordx4 v130, s[68:69]
	s_add_i32 m0, s70, 0x2000
	s_nop 0
	global_load_lds_dwordx4 v168, s[68:69]
	s_add_u32 s100, s30, s34
	s_addc_u32 s101, s31, s35
	s_mov_b32 m0, s45
	s_nop 0
	global_load_lds_dwordx4 v176, s[30:31]
	s_mov_b32 m0, s46
	s_nop 0
	global_load_lds_dwordx4 v170, s[30:31]
	s_waitcnt vmcnt(8)
	s_waitcnt lgkmcnt(0)
	s_barrier
	s_setprio 1
	s_waitcnt lgkmcnt(0)
	v_mfma_f32_16x16x32_bf16 v[62:65], v[106:109], v[164:167], v[62:65]
	v_mfma_f32_16x16x32_bf16 v[58:61], v[114:117], v[164:167], v[58:61]
	v_mfma_f32_16x16x32_bf16 v[46:49], v[106:109], v[186:189], v[46:49]
	v_mfma_f32_16x16x32_bf16 v[42:45], v[114:117], v[186:189], v[42:45]
	v_mfma_f32_16x16x32_bf16 v[30:33], v[106:109], v[208:211], v[30:33]
	v_mfma_f32_16x16x32_bf16 v[26:29], v[114:117], v[208:211], v[26:29]
	v_mfma_f32_16x16x32_bf16 v[14:17], v[106:109], v[226:229], v[14:17]
	v_mfma_f32_16x16x32_bf16 v[10:13], v[114:117], v[226:229], v[10:13]
	v_mfma_f32_16x16x32_bf16 v[62:65], v[110:113], v[182:185], v[62:65]
	v_mfma_f32_16x16x32_bf16 v[58:61], v[118:121], v[182:185], v[58:61]
	v_mfma_f32_16x16x32_bf16 v[46:49], v[110:113], v[190:193], v[46:49]
	v_mfma_f32_16x16x32_bf16 v[42:45], v[118:121], v[190:193], v[42:45]
	v_mfma_f32_16x16x32_bf16 v[30:33], v[110:113], v[222:225], v[30:33]
	v_mfma_f32_16x16x32_bf16 v[26:29], v[118:121], v[222:225], v[26:29]
	v_mfma_f32_16x16x32_bf16 v[14:17], v[110:113], v[230:233], v[14:17]
	v_mfma_f32_16x16x32_bf16 v[10:13], v[118:121], v[230:233], v[10:13]
	s_setprio 0
	s_setprio 1
	v_mfma_f32_16x16x32_bf16 v[54:57], v[148:151], v[164:167], v[54:57]
	v_mfma_f32_16x16x32_bf16 v[50:53], v[156:159], v[164:167], v[50:53]
	v_mfma_f32_16x16x32_bf16 v[38:41], v[148:151], v[186:189], v[38:41]
	v_mfma_f32_16x16x32_bf16 v[34:37], v[156:159], v[186:189], v[34:37]
	v_mfma_f32_16x16x32_bf16 v[22:25], v[148:151], v[208:211], v[22:25]
	v_mfma_f32_16x16x32_bf16 v[18:21], v[156:159], v[208:211], v[18:21]
	v_mfma_f32_16x16x32_bf16 v[6:9], v[148:151], v[226:229], v[6:9]
	v_mfma_f32_16x16x32_bf16 v[2:5], v[156:159], v[226:229], v[2:5]
	v_mfma_f32_16x16x32_bf16 v[54:57], v[152:155], v[182:185], v[54:57]
	v_mfma_f32_16x16x32_bf16 v[50:53], v[160:163], v[182:185], v[50:53]
	v_mfma_f32_16x16x32_bf16 v[38:41], v[152:155], v[190:193], v[38:41]
	v_mfma_f32_16x16x32_bf16 v[34:37], v[160:163], v[190:193], v[34:37]
	v_mfma_f32_16x16x32_bf16 v[22:25], v[152:155], v[222:225], v[22:25]
	v_mfma_f32_16x16x32_bf16 v[18:21], v[160:163], v[222:225], v[18:21]
	v_mfma_f32_16x16x32_bf16 v[6:9], v[152:155], v[230:233], v[6:9]
	v_mfma_f32_16x16x32_bf16 v[2:5], v[160:163], v[230:233], v[2:5]
	s_setprio 0
	s_barrier
	s_add_i32 s68, 0, 0x18000
	s_add_i32 s69, 0, 0x1c000
	v_add_u32_e32 v118, s68, v195
	v_add_u32_e32 v160, s69, v195
	ds_read_b128 v[106:109], v118
	ds_read_b128 v[110:113], v118 offset:1024
	ds_read_b128 v[114:117], v118 offset:2048
	ds_read_b128 v[118:121], v118 offset:3072
	ds_read_b128 v[148:151], v160
	ds_read_b128 v[152:155], v160 offset:1024
	ds_read_b128 v[156:159], v160 offset:2048
	ds_read_b128 v[160:163], v160 offset:3072
	s_add_u32 s30, s30, 0x80000
	s_addc_u32 s31, s31, 0
	s_mov_b32 m0, s47
	ds_read_b128 v[164:167], v197 offset:32768
	ds_read_b128 v[182:185], v197 offset:33792
	ds_read_b128 v[186:189], v197 offset:34816
	ds_read_b128 v[190:193], v197 offset:35840
	ds_read_b128 v[208:211], v197 offset:36864
	ds_read_b128 v[222:225], v197 offset:37888
	ds_read_b128 v[226:229], v197 offset:38912
	ds_read_b128 v[230:233], v197 offset:39936
	global_load_lds_dwordx4 v176, s[30:31]
	s_mov_b32 m0, s48
	s_nop 0
	global_load_lds_dwordx4 v170, s[30:31]
	s_waitcnt vmcnt(8)
	s_waitcnt lgkmcnt(0)
	s_barrier
	s_setprio 1
	s_waitcnt lgkmcnt(0)
	v_mfma_f32_16x16x32_bf16 v[144:147], v[106:109], v[164:167], v[144:147]
	v_mfma_f32_16x16x32_bf16 v[140:143], v[114:117], v[164:167], v[140:143]
	v_mfma_f32_16x16x32_bf16 v[136:139], v[106:109], v[186:189], v[136:139]
	v_mfma_f32_16x16x32_bf16 v[132:135], v[114:117], v[186:189], v[132:135]
	v_mfma_f32_16x16x32_bf16 v[94:97], v[106:109], v[208:211], v[94:97]
	v_mfma_f32_16x16x32_bf16 v[90:93], v[114:117], v[208:211], v[90:93]
	v_mfma_f32_16x16x32_bf16 v[78:81], v[106:109], v[226:229], v[78:81]
	v_mfma_f32_16x16x32_bf16 v[74:77], v[114:117], v[226:229], v[74:77]
	v_mfma_f32_16x16x32_bf16 v[144:147], v[110:113], v[182:185], v[144:147]
	v_mfma_f32_16x16x32_bf16 v[140:143], v[118:121], v[182:185], v[140:143]
	v_mfma_f32_16x16x32_bf16 v[136:139], v[110:113], v[190:193], v[136:139]
	v_mfma_f32_16x16x32_bf16 v[132:135], v[118:121], v[190:193], v[132:135]
	v_mfma_f32_16x16x32_bf16 v[94:97], v[110:113], v[222:225], v[94:97]
	v_mfma_f32_16x16x32_bf16 v[90:93], v[118:121], v[222:225], v[90:93]
	v_mfma_f32_16x16x32_bf16 v[78:81], v[110:113], v[230:233], v[78:81]
	v_mfma_f32_16x16x32_bf16 v[74:77], v[118:121], v[230:233], v[74:77]
	s_setprio 0
	s_setprio 1
	v_mfma_f32_16x16x32_bf16 v[126:129], v[148:151], v[164:167], v[126:129]
	v_mfma_f32_16x16x32_bf16 v[122:125], v[156:159], v[164:167], v[122:125]
	v_mfma_f32_16x16x32_bf16 v[102:105], v[148:151], v[186:189], v[102:105]
	v_mfma_f32_16x16x32_bf16 v[98:101], v[156:159], v[186:189], v[98:101]
	v_mfma_f32_16x16x32_bf16 v[86:89], v[148:151], v[208:211], v[86:89]
	v_mfma_f32_16x16x32_bf16 v[82:85], v[156:159], v[208:211], v[82:85]
	v_mfma_f32_16x16x32_bf16 v[70:73], v[148:151], v[226:229], v[70:73]
	v_mfma_f32_16x16x32_bf16 v[66:69], v[156:159], v[226:229], v[66:69]
	v_mfma_f32_16x16x32_bf16 v[126:129], v[152:155], v[182:185], v[126:129]
	v_mfma_f32_16x16x32_bf16 v[122:125], v[160:163], v[182:185], v[122:125]
	v_mfma_f32_16x16x32_bf16 v[102:105], v[152:155], v[190:193], v[102:105]
	v_mfma_f32_16x16x32_bf16 v[98:101], v[160:163], v[190:193], v[98:101]
	v_mfma_f32_16x16x32_bf16 v[86:89], v[152:155], v[222:225], v[86:89]
	v_mfma_f32_16x16x32_bf16 v[82:85], v[160:163], v[222:225], v[82:85]
	v_mfma_f32_16x16x32_bf16 v[70:73], v[152:155], v[230:233], v[70:73]
	v_mfma_f32_16x16x32_bf16 v[66:69], v[160:163], v[230:233], v[66:69]
	s_setprio 0
	s_barrier
	s_add_i32 s30, s68, s44
	s_mov_b32 m0, s30
	ds_read_b128 v[164:167], v197 offset:49152
	ds_read_b128 v[182:185], v197 offset:50176
	ds_read_b128 v[186:189], v197 offset:51200
	ds_read_b128 v[190:193], v197 offset:52224
	ds_read_b128 v[208:211], v197 offset:53248
	ds_read_b128 v[222:225], v197 offset:54272
	ds_read_b128 v[226:229], v197 offset:55296
	ds_read_b128 v[230:233], v197 offset:56320
	global_load_lds_dwordx4 v130, s[98:99]
	s_add_i32 m0, s30, 0x2000
	s_add_u32 s28, s28, 0x80080
	s_addc_u32 s29, s29, 0
	s_add_i32 s30, s69, s44
	global_load_lds_dwordx4 v168, s[98:99]
	s_mov_b32 m0, s30
	s_nop 0
	global_load_lds_dwordx4 v130, s[28:29]
	s_add_i32 m0, s30, 0x2000
	s_nop 0
	global_load_lds_dwordx4 v168, s[28:29]
	s_mov_b32 m0, s54
	s_nop 0
	global_load_lds_dwordx4 v176, s[100:101]
	s_mov_b32 m0, s55
	s_nop 0
	global_load_lds_dwordx4 v170, s[100:101]
	s_waitcnt vmcnt(8)
	s_waitcnt lgkmcnt(0)
	s_barrier
	s_setprio 1
	s_waitcnt lgkmcnt(0)
	v_mfma_f32_16x16x32_bf16 v[62:65], v[106:109], v[164:167], v[62:65]
	v_mfma_f32_16x16x32_bf16 v[58:61], v[114:117], v[164:167], v[58:61]
	v_mfma_f32_16x16x32_bf16 v[46:49], v[106:109], v[186:189], v[46:49]
	v_mfma_f32_16x16x32_bf16 v[42:45], v[114:117], v[186:189], v[42:45]
	v_mfma_f32_16x16x32_bf16 v[30:33], v[106:109], v[208:211], v[30:33]
	v_mfma_f32_16x16x32_bf16 v[26:29], v[114:117], v[208:211], v[26:29]
	v_mfma_f32_16x16x32_bf16 v[14:17], v[106:109], v[226:229], v[14:17]
	v_mfma_f32_16x16x32_bf16 v[10:13], v[114:117], v[226:229], v[10:13]
	v_mfma_f32_16x16x32_bf16 v[62:65], v[110:113], v[182:185], v[62:65]
	v_mfma_f32_16x16x32_bf16 v[58:61], v[118:121], v[182:185], v[58:61]
	v_mfma_f32_16x16x32_bf16 v[46:49], v[110:113], v[190:193], v[46:49]
	v_mfma_f32_16x16x32_bf16 v[42:45], v[118:121], v[190:193], v[42:45]
	v_mfma_f32_16x16x32_bf16 v[30:33], v[110:113], v[222:225], v[30:33]
	v_mfma_f32_16x16x32_bf16 v[26:29], v[118:121], v[222:225], v[26:29]
	v_mfma_f32_16x16x32_bf16 v[14:17], v[110:113], v[230:233], v[14:17]
	v_mfma_f32_16x16x32_bf16 v[10:13], v[118:121], v[230:233], v[10:13]
	s_setprio 0
	s_setprio 1
	v_mfma_f32_16x16x32_bf16 v[54:57], v[148:151], v[164:167], v[54:57]
	v_mfma_f32_16x16x32_bf16 v[50:53], v[156:159], v[164:167], v[50:53]
	v_mfma_f32_16x16x32_bf16 v[38:41], v[148:151], v[186:189], v[38:41]
	v_mfma_f32_16x16x32_bf16 v[34:37], v[156:159], v[186:189], v[34:37]
	v_mfma_f32_16x16x32_bf16 v[22:25], v[148:151], v[208:211], v[22:25]
	v_mfma_f32_16x16x32_bf16 v[18:21], v[156:159], v[208:211], v[18:21]
	v_mfma_f32_16x16x32_bf16 v[6:9], v[148:151], v[226:229], v[6:9]
	v_mfma_f32_16x16x32_bf16 v[2:5], v[156:159], v[226:229], v[2:5]
	v_mfma_f32_16x16x32_bf16 v[54:57], v[152:155], v[182:185], v[54:57]
	v_mfma_f32_16x16x32_bf16 v[50:53], v[160:163], v[182:185], v[50:53]
	v_mfma_f32_16x16x32_bf16 v[38:41], v[152:155], v[190:193], v[38:41]
	v_mfma_f32_16x16x32_bf16 v[34:37], v[160:163], v[190:193], v[34:37]
	v_mfma_f32_16x16x32_bf16 v[22:25], v[152:155], v[222:225], v[22:25]
	v_mfma_f32_16x16x32_bf16 v[18:21], v[160:163], v[222:225], v[18:21]
	v_mfma_f32_16x16x32_bf16 v[6:9], v[152:155], v[230:233], v[6:9]
	v_mfma_f32_16x16x32_bf16 v[2:5], v[160:163], v[230:233], v[2:5]
	s_setprio 0
	s_barrier
	s_add_i32 s63, s63, 2
	s_add_u32 s61, s61, 0x100
	s_addc_u32 s62, s62, 0
	s_add_u32 s24, s24, 0x100
	s_addc_u32 s25, s25, 0
	s_cmp_gt_u32 s63, 29
	s_cbranch_scc0 .LBB0_1029
	s_and_b64 vcc, exec, s[8:9]
	s_cbranch_vccz .LBB0_1032
	s_barrier

.LBB0_1049:
	s_add_u32 s24, s16, 0x2fff00
	s_addc_u32 s25, s17, 0
	s_cmp_eq_u32 s61, 28
	s_cselect_b32 s30, s57, s24
	s_cselect_b32 s31, s11, s25
	s_cselect_b32 s28, s58, s59
	s_cselect_b32 s29, s9, s60
	s_add_u32 s24, s30, 0x300000
	s_addc_u32 s25, s31, 0
	s_add_i32 s62, 0, 0x10000
	s_add_i32 s68, 0, 0x14000
	v_add_u32_e32 v118, s62, v210
	v_add_u32_e32 v160, s68, v210
	ds_read_b128 v[106:109], v118
	ds_read_b128 v[110:113], v118 offset:1024
	ds_read_b128 v[114:117], v118 offset:2048
	ds_read_b128 v[118:121], v118 offset:3072
	ds_read_b128 v[148:151], v160
	ds_read_b128 v[152:155], v160 offset:1024
	ds_read_b128 v[156:159], v160 offset:2048
	ds_read_b128 v[160:163], v160 offset:3072
	ds_read_b64_tr_b16 v[164:165], v194 offset:0
	ds_read_b64_tr_b16 v[166:167], v195 offset:0
	ds_read_b64_tr_b16 v[182:183], v194 offset:0x2000
	ds_read_b64_tr_b16 v[184:185], v195 offset:0x2000
	ds_read_b64_tr_b16 v[186:187], v196 offset:0
	ds_read_b64_tr_b16 v[188:189], v197 offset:0
	ds_read_b64_tr_b16 v[190:191], v196 offset:0x2000
	ds_read_b64_tr_b16 v[192:193], v197 offset:0x2000
	ds_read_b64_tr_b16 v[222:223], v198 offset:0
	ds_read_b64_tr_b16 v[224:225], v199 offset:0
	ds_read_b64_tr_b16 v[226:227], v198 offset:0x2000
	ds_read_b64_tr_b16 v[228:229], v199 offset:0x2000
	ds_read_b64_tr_b16 v[230:231], v208 offset:0
	ds_read_b64_tr_b16 v[232:233], v209 offset:0
	ds_read_b64_tr_b16 v[234:235], v208 offset:0x2000
	ds_read_b64_tr_b16 v[236:237], v209 offset:0x2000
	s_add_i32 m0, s43, 0xc000
	s_nop 0
	global_load_lds_dwordx4 v180, s[16:17]
	s_add_i32 m0, s43, 0xe000
	s_nop 0
	global_load_lds_dwordx4 v178, s[16:17]
	s_waitcnt vmcnt(8)
	s_waitcnt lgkmcnt(0)
	s_barrier
	s_setprio 1
	s_waitcnt lgkmcnt(0)
	v_mfma_f32_16x16x32_bf16 v[144:147], v[106:109], v[164:167], v[144:147]
	v_mfma_f32_16x16x32_bf16 v[140:143], v[114:117], v[164:167], v[140:143]
	v_mfma_f32_16x16x32_bf16 v[136:139], v[106:109], v[186:189], v[136:139]
	v_mfma_f32_16x16x32_bf16 v[132:135], v[114:117], v[186:189], v[132:135]
	v_mfma_f32_16x16x32_bf16 v[94:97], v[106:109], v[222:225], v[94:97]
	v_mfma_f32_16x16x32_bf16 v[90:93], v[114:117], v[222:225], v[90:93]
	v_mfma_f32_16x16x32_bf16 v[78:81], v[106:109], v[230:233], v[78:81]
	v_mfma_f32_16x16x32_bf16 v[74:77], v[114:117], v[230:233], v[74:77]
	v_mfma_f32_16x16x32_bf16 v[144:147], v[110:113], v[182:185], v[144:147]
	v_mfma_f32_16x16x32_bf16 v[140:143], v[118:121], v[182:185], v[140:143]
	v_mfma_f32_16x16x32_bf16 v[136:139], v[110:113], v[190:193], v[136:139]
	v_mfma_f32_16x16x32_bf16 v[132:135], v[118:121], v[190:193], v[132:135]
	v_mfma_f32_16x16x32_bf16 v[94:97], v[110:113], v[226:229], v[94:97]
	v_mfma_f32_16x16x32_bf16 v[90:93], v[118:121], v[226:229], v[90:93]
	v_mfma_f32_16x16x32_bf16 v[78:81], v[110:113], v[234:237], v[78:81]
	v_mfma_f32_16x16x32_bf16 v[74:77], v[118:121], v[234:237], v[74:77]
	s_setprio 0
	s_setprio 1
	v_mfma_f32_16x16x32_bf16 v[126:129], v[148:151], v[164:167], v[126:129]
	v_mfma_f32_16x16x32_bf16 v[122:125], v[156:159], v[164:167], v[122:125]
	v_mfma_f32_16x16x32_bf16 v[102:105], v[148:151], v[186:189], v[102:105]
	v_mfma_f32_16x16x32_bf16 v[98:101], v[156:159], v[186:189], v[98:101]
	v_mfma_f32_16x16x32_bf16 v[86:89], v[148:151], v[222:225], v[86:89]
	v_mfma_f32_16x16x32_bf16 v[82:85], v[156:159], v[222:225], v[82:85]
	v_mfma_f32_16x16x32_bf16 v[70:73], v[148:151], v[230:233], v[70:73]
	v_mfma_f32_16x16x32_bf16 v[66:69], v[156:159], v[230:233], v[66:69]
	v_mfma_f32_16x16x32_bf16 v[126:129], v[152:155], v[182:185], v[126:129]
	v_mfma_f32_16x16x32_bf16 v[122:125], v[160:163], v[182:185], v[122:125]
	v_mfma_f32_16x16x32_bf16 v[102:105], v[152:155], v[190:193], v[102:105]
	v_mfma_f32_16x16x32_bf16 v[98:101], v[160:163], v[190:193], v[98:101]
	v_mfma_f32_16x16x32_bf16 v[86:89], v[152:155], v[226:229], v[86:89]
	v_mfma_f32_16x16x32_bf16 v[82:85], v[160:163], v[226:229], v[82:85]
	v_mfma_f32_16x16x32_bf16 v[70:73], v[152:155], v[234:237], v[70:73]
	v_mfma_f32_16x16x32_bf16 v[66:69], v[160:163], v[234:237], v[66:69]
	s_setprio 0
	s_barrier
	ds_read_b64_tr_b16 v[164:165], v194 offset:0x4000
	ds_read_b64_tr_b16 v[166:167], v195 offset:0x4000
	ds_read_b64_tr_b16 v[182:183], v194 offset:0x6000
	ds_read_b64_tr_b16 v[184:185], v195 offset:0x6000
	ds_read_b64_tr_b16 v[186:187], v196 offset:0x4000
	ds_read_b64_tr_b16 v[188:189], v197 offset:0x4000
	ds_read_b64_tr_b16 v[190:191], v196 offset:0x6000
	ds_read_b64_tr_b16 v[192:193], v197 offset:0x6000
	ds_read_b64_tr_b16 v[222:223], v198 offset:0x4000
	ds_read_b64_tr_b16 v[224:225], v199 offset:0x4000
	ds_read_b64_tr_b16 v[226:227], v198 offset:0x6000
	ds_read_b64_tr_b16 v[228:229], v199 offset:0x6000
	ds_read_b64_tr_b16 v[230:231], v208 offset:0x4000
	ds_read_b64_tr_b16 v[232:233], v209 offset:0x4000
	ds_read_b64_tr_b16 v[234:235], v208 offset:0x6000
	s_add_i32 s62, s62, s42
	ds_read_b64_tr_b16 v[236:237], v209 offset:0x6000
	s_add_u32 s100, s28, s34
	s_addc_u32 s101, s29, s35
	s_mov_b32 m0, s62
	s_nop 0
	global_load_lds_dwordx4 v130, s[28:29]
	s_add_i32 m0, s62, 0x2000
	s_add_u32 s62, s28, 0x80000
	s_addc_u32 s63, s29, 0
	s_add_i32 s68, s68, s42
	global_load_lds_dwordx4 v170, s[28:29]
	s_mov_b32 m0, s68
	s_nop 0
	global_load_lds_dwordx4 v130, s[62:63]
	s_add_i32 m0, s68, 0x2000
	s_nop 0
	global_load_lds_dwordx4 v170, s[62:63]
	s_add_u32 s98, s30, s82
	s_addc_u32 s99, s31, s83
	s_mov_b32 m0, s43
	s_nop 0
	global_load_lds_dwordx4 v176, s[30:31]
	s_mov_b32 m0, s44
	s_nop 0
	global_load_lds_dwordx4 v168, s[30:31]
	s_waitcnt vmcnt(8)
	s_waitcnt lgkmcnt(0)
	s_barrier
	s_setprio 1
	v_mfma_f32_16x16x32_bf16 v[62:65], v[106:109], v[164:167], v[62:65]
	v_mfma_f32_16x16x32_bf16 v[58:61], v[114:117], v[164:167], v[58:61]
	v_mfma_f32_16x16x32_bf16 v[46:49], v[106:109], v[186:189], v[46:49]
	v_mfma_f32_16x16x32_bf16 v[42:45], v[114:117], v[186:189], v[42:45]
	v_mfma_f32_16x16x32_bf16 v[30:33], v[106:109], v[222:225], v[30:33]
	v_mfma_f32_16x16x32_bf16 v[26:29], v[114:117], v[222:225], v[26:29]
	v_mfma_f32_16x16x32_bf16 v[14:17], v[106:109], v[230:233], v[14:17]
	v_mfma_f32_16x16x32_bf16 v[10:13], v[114:117], v[230:233], v[10:13]
	v_mfma_f32_16x16x32_bf16 v[62:65], v[110:113], v[182:185], v[62:65]
	v_mfma_f32_16x16x32_bf16 v[58:61], v[118:121], v[182:185], v[58:61]
	v_mfma_f32_16x16x32_bf16 v[46:49], v[110:113], v[190:193], v[46:49]
	v_mfma_f32_16x16x32_bf16 v[42:45], v[118:121], v[190:193], v[42:45]
	v_mfma_f32_16x16x32_bf16 v[30:33], v[110:113], v[226:229], v[30:33]
	v_mfma_f32_16x16x32_bf16 v[26:29], v[118:121], v[226:229], v[26:29]
	v_mfma_f32_16x16x32_bf16 v[14:17], v[110:113], v[234:237], v[14:17]
	v_mfma_f32_16x16x32_bf16 v[10:13], v[118:121], v[234:237], v[10:13]
	s_setprio 0
	s_setprio 1
	v_mfma_f32_16x16x32_bf16 v[54:57], v[148:151], v[164:167], v[54:57]
	v_mfma_f32_16x16x32_bf16 v[50:53], v[156:159], v[164:167], v[50:53]
	v_mfma_f32_16x16x32_bf16 v[38:41], v[148:151], v[186:189], v[38:41]
	v_mfma_f32_16x16x32_bf16 v[34:37], v[156:159], v[186:189], v[34:37]
	v_mfma_f32_16x16x32_bf16 v[22:25], v[148:151], v[222:225], v[22:25]
	v_mfma_f32_16x16x32_bf16 v[18:21], v[156:159], v[222:225], v[18:21]
	v_mfma_f32_16x16x32_bf16 v[6:9], v[148:151], v[230:233], v[6:9]
	v_mfma_f32_16x16x32_bf16 v[2:5], v[156:159], v[230:233], v[2:5]
	v_mfma_f32_16x16x32_bf16 v[54:57], v[152:155], v[182:185], v[54:57]
	v_mfma_f32_16x16x32_bf16 v[50:53], v[160:163], v[182:185], v[50:53]
	v_mfma_f32_16x16x32_bf16 v[38:41], v[152:155], v[190:193], v[38:41]
	v_mfma_f32_16x16x32_bf16 v[34:37], v[160:163], v[190:193], v[34:37]
	v_mfma_f32_16x16x32_bf16 v[22:25], v[152:155], v[226:229], v[22:25]
	v_mfma_f32_16x16x32_bf16 v[18:21], v[160:163], v[226:229], v[18:21]
	v_mfma_f32_16x16x32_bf16 v[6:9], v[152:155], v[234:237], v[6:9]
	v_mfma_f32_16x16x32_bf16 v[2:5], v[160:163], v[234:237], v[2:5]
	s_setprio 0
	s_barrier
	s_add_i32 s30, 0, 0x18000
	s_add_i32 s31, 0, 0x1c000
	v_add_u32_e32 v118, s30, v210
	v_add_u32_e32 v160, s31, v210
	ds_read_b128 v[106:109], v118
	ds_read_b128 v[110:113], v118 offset:1024
	ds_read_b128 v[114:117], v118 offset:2048
	ds_read_b128 v[118:121], v118 offset:3072
	ds_read_b128 v[148:151], v160
	ds_read_b128 v[152:155], v160 offset:1024
	ds_read_b128 v[156:159], v160 offset:2048
	ds_read_b128 v[160:163], v160 offset:3072
	ds_read_b64_tr_b16 v[164:165], v194 offset:0x8000
	ds_read_b64_tr_b16 v[166:167], v195 offset:0x8000
	ds_read_b64_tr_b16 v[182:183], v194 offset:0xa000
	ds_read_b64_tr_b16 v[184:185], v195 offset:0xa000
	ds_read_b64_tr_b16 v[186:187], v196 offset:0x8000
	ds_read_b64_tr_b16 v[188:189], v197 offset:0x8000
	ds_read_b64_tr_b16 v[190:191], v196 offset:0xa000
	ds_read_b64_tr_b16 v[192:193], v197 offset:0xa000
	ds_read_b64_tr_b16 v[222:223], v198 offset:0x8000
	ds_read_b64_tr_b16 v[224:225], v199 offset:0x8000
	ds_read_b64_tr_b16 v[226:227], v198 offset:0xa000
	ds_read_b64_tr_b16 v[228:229], v199 offset:0xa000
	ds_read_b64_tr_b16 v[230:231], v208 offset:0x8000
	ds_read_b64_tr_b16 v[232:233], v209 offset:0x8000
	ds_read_b64_tr_b16 v[234:235], v208 offset:0xa000
	s_mov_b32 m0, s45
	ds_read_b64_tr_b16 v[236:237], v209 offset:0xa000
	global_load_lds_dwordx4 v176, s[98:99]
	s_mov_b32 m0, s46
	s_nop 0
	global_load_lds_dwordx4 v168, s[98:99]
	s_waitcnt vmcnt(8)
	s_waitcnt lgkmcnt(0)
	s_barrier
	s_setprio 1
	s_waitcnt lgkmcnt(0)
	v_mfma_f32_16x16x32_bf16 v[144:147], v[106:109], v[164:167], v[144:147]
	v_mfma_f32_16x16x32_bf16 v[140:143], v[114:117], v[164:167], v[140:143]
	v_mfma_f32_16x16x32_bf16 v[136:139], v[106:109], v[186:189], v[136:139]
	v_mfma_f32_16x16x32_bf16 v[132:135], v[114:117], v[186:189], v[132:135]
	v_mfma_f32_16x16x32_bf16 v[94:97], v[106:109], v[222:225], v[94:97]
	v_mfma_f32_16x16x32_bf16 v[90:93], v[114:117], v[222:225], v[90:93]
	v_mfma_f32_16x16x32_bf16 v[78:81], v[106:109], v[230:233], v[78:81]
	v_mfma_f32_16x16x32_bf16 v[74:77], v[114:117], v[230:233], v[74:77]
	v_mfma_f32_16x16x32_bf16 v[144:147], v[110:113], v[182:185], v[144:147]
	v_mfma_f32_16x16x32_bf16 v[140:143], v[118:121], v[182:185], v[140:143]
	v_mfma_f32_16x16x32_bf16 v[136:139], v[110:113], v[190:193], v[136:139]
	v_mfma_f32_16x16x32_bf16 v[132:135], v[118:121], v[190:193], v[132:135]
	v_mfma_f32_16x16x32_bf16 v[94:97], v[110:113], v[226:229], v[94:97]
	v_mfma_f32_16x16x32_bf16 v[90:93], v[118:121], v[226:229], v[90:93]
	v_mfma_f32_16x16x32_bf16 v[78:81], v[110:113], v[234:237], v[78:81]
	v_mfma_f32_16x16x32_bf16 v[74:77], v[118:121], v[234:237], v[74:77]
	s_setprio 0
	s_setprio 1
	v_mfma_f32_16x16x32_bf16 v[126:129], v[148:151], v[164:167], v[126:129]
	v_mfma_f32_16x16x32_bf16 v[122:125], v[156:159], v[164:167], v[122:125]
	v_mfma_f32_16x16x32_bf16 v[102:105], v[148:151], v[186:189], v[102:105]
	v_mfma_f32_16x16x32_bf16 v[98:101], v[156:159], v[186:189], v[98:101]
	v_mfma_f32_16x16x32_bf16 v[86:89], v[148:151], v[222:225], v[86:89]
	v_mfma_f32_16x16x32_bf16 v[82:85], v[156:159], v[222:225], v[82:85]
	v_mfma_f32_16x16x32_bf16 v[70:73], v[148:151], v[230:233], v[70:73]
	v_mfma_f32_16x16x32_bf16 v[66:69], v[156:159], v[230:233], v[66:69]
	v_mfma_f32_16x16x32_bf16 v[126:129], v[152:155], v[182:185], v[126:129]
	v_mfma_f32_16x16x32_bf16 v[122:125], v[160:163], v[182:185], v[122:125]
	v_mfma_f32_16x16x32_bf16 v[102:105], v[152:155], v[190:193], v[102:105]
	v_mfma_f32_16x16x32_bf16 v[98:101], v[160:163], v[190:193], v[98:101]
	v_mfma_f32_16x16x32_bf16 v[86:89], v[152:155], v[226:229], v[86:89]
	v_mfma_f32_16x16x32_bf16 v[82:85], v[160:163], v[226:229], v[82:85]
	v_mfma_f32_16x16x32_bf16 v[70:73], v[152:155], v[234:237], v[70:73]
	v_mfma_f32_16x16x32_bf16 v[66:69], v[160:163], v[234:237], v[66:69]
	s_setprio 0
	s_barrier
	ds_read_b64_tr_b16 v[164:165], v194 offset:0xc000
	ds_read_b64_tr_b16 v[166:167], v195 offset:0xc000
	ds_read_b64_tr_b16 v[182:183], v194 offset:0xe000
	ds_read_b64_tr_b16 v[184:185], v195 offset:0xe000
	ds_read_b64_tr_b16 v[186:187], v196 offset:0xc000
	ds_read_b64_tr_b16 v[188:189], v197 offset:0xc000
	ds_read_b64_tr_b16 v[190:191], v196 offset:0xe000
	ds_read_b64_tr_b16 v[192:193], v197 offset:0xe000
	ds_read_b64_tr_b16 v[222:223], v198 offset:0xc000
	ds_read_b64_tr_b16 v[224:225], v199 offset:0xc000
	ds_read_b64_tr_b16 v[226:227], v198 offset:0xe000
	ds_read_b64_tr_b16 v[228:229], v199 offset:0xe000
	ds_read_b64_tr_b16 v[230:231], v208 offset:0xc000
	ds_read_b64_tr_b16 v[232:233], v209 offset:0xc000
	ds_read_b64_tr_b16 v[234:235], v208 offset:0xe000
	s_add_i32 s30, s30, s42
	ds_read_b64_tr_b16 v[236:237], v209 offset:0xe000
	s_mov_b32 m0, s30
	s_nop 0
	global_load_lds_dwordx4 v130, s[100:101]
	s_add_i32 m0, s30, 0x2000
	s_add_u32 s28, s28, 0x80080
	s_addc_u32 s29, s29, 0
	s_add_i32 s30, s31, s42
	global_load_lds_dwordx4 v170, s[100:101]
	s_mov_b32 m0, s30
	s_nop 0
	global_load_lds_dwordx4 v130, s[28:29]
	s_add_i32 m0, s30, 0x2000
	s_nop 0
	global_load_lds_dwordx4 v170, s[28:29]
	s_mov_b32 m0, s48
	s_nop 0
	global_load_lds_dwordx4 v176, s[24:25]
	s_mov_b32 m0, s49
	s_nop 0
	global_load_lds_dwordx4 v168, s[24:25]
	s_waitcnt vmcnt(8)
	s_waitcnt lgkmcnt(0)
	s_barrier
	s_setprio 1
	v_mfma_f32_16x16x32_bf16 v[62:65], v[106:109], v[164:167], v[62:65]
	v_mfma_f32_16x16x32_bf16 v[58:61], v[114:117], v[164:167], v[58:61]
	v_mfma_f32_16x16x32_bf16 v[46:49], v[106:109], v[186:189], v[46:49]
	v_mfma_f32_16x16x32_bf16 v[42:45], v[114:117], v[186:189], v[42:45]
	v_mfma_f32_16x16x32_bf16 v[30:33], v[106:109], v[222:225], v[30:33]
	v_mfma_f32_16x16x32_bf16 v[26:29], v[114:117], v[222:225], v[26:29]
	v_mfma_f32_16x16x32_bf16 v[14:17], v[106:109], v[230:233], v[14:17]
	v_mfma_f32_16x16x32_bf16 v[10:13], v[114:117], v[230:233], v[10:13]
	v_mfma_f32_16x16x32_bf16 v[62:65], v[110:113], v[182:185], v[62:65]
	v_mfma_f32_16x16x32_bf16 v[58:61], v[118:121], v[182:185], v[58:61]
	v_mfma_f32_16x16x32_bf16 v[46:49], v[110:113], v[190:193], v[46:49]
	v_mfma_f32_16x16x32_bf16 v[42:45], v[118:121], v[190:193], v[42:45]
	v_mfma_f32_16x16x32_bf16 v[30:33], v[110:113], v[226:229], v[30:33]
	v_mfma_f32_16x16x32_bf16 v[26:29], v[118:121], v[226:229], v[26:29]
	v_mfma_f32_16x16x32_bf16 v[14:17], v[110:113], v[234:237], v[14:17]
	v_mfma_f32_16x16x32_bf16 v[10:13], v[118:121], v[234:237], v[10:13]
	s_setprio 0
	s_setprio 1
	v_mfma_f32_16x16x32_bf16 v[54:57], v[148:151], v[164:167], v[54:57]
	v_mfma_f32_16x16x32_bf16 v[50:53], v[156:159], v[164:167], v[50:53]
	v_mfma_f32_16x16x32_bf16 v[38:41], v[148:151], v[186:189], v[38:41]
	v_mfma_f32_16x16x32_bf16 v[34:37], v[156:159], v[186:189], v[34:37]
	v_mfma_f32_16x16x32_bf16 v[22:25], v[148:151], v[222:225], v[22:25]
	v_mfma_f32_16x16x32_bf16 v[18:21], v[156:159], v[222:225], v[18:21]
	v_mfma_f32_16x16x32_bf16 v[6:9], v[148:151], v[230:233], v[6:9]
	v_mfma_f32_16x16x32_bf16 v[2:5], v[156:159], v[230:233], v[2:5]
	v_mfma_f32_16x16x32_bf16 v[54:57], v[152:155], v[182:185], v[54:57]
	v_mfma_f32_16x16x32_bf16 v[50:53], v[160:163], v[182:185], v[50:53]
	v_mfma_f32_16x16x32_bf16 v[38:41], v[152:155], v[190:193], v[38:41]
	v_mfma_f32_16x16x32_bf16 v[34:37], v[160:163], v[190:193], v[34:37]
	v_mfma_f32_16x16x32_bf16 v[22:25], v[152:155], v[226:229], v[22:25]
	v_mfma_f32_16x16x32_bf16 v[18:21], v[160:163], v[226:229], v[18:21]
	v_mfma_f32_16x16x32_bf16 v[6:9], v[152:155], v[234:237], v[6:9]
	v_mfma_f32_16x16x32_bf16 v[2:5], v[160:163], v[234:237], v[2:5]
	s_setprio 0
	s_barrier
	s_add_i32 s61, s61, 2
	s_add_u32 s59, s59, 0x100
	s_addc_u32 s60, s60, 0
	s_add_u32 s16, s16, 0x600000
	s_addc_u32 s17, s17, 0
	s_cmp_gt_u32 s61, 29
	s_cbranch_scc0 .LBB0_1049
	s_and_b64 vcc, exec, s[6:7]
	s_cbranch_vccz .LBB0_1052
	s_barrier

.LBB0_1188:
	s_add_u32 s16, s14, 0xfff80080
	s_addc_u32 s17, s15, -1
	s_add_i32 s60, 0, 0x10000
	s_cmp_eq_u32 s59, 28
	s_cselect_b32 s25, s9, s17
	s_cselect_b32 s24, s55, s16
	v_add_u32_e32 v170, s60, v160
	s_cselect_b32 s17, s7, s58
	s_cselect_b32 s16, s56, s57
	s_add_i32 s62, 0, 0x14000
	ds_read_b128 v[162:165], v170
	ds_read_b128 v[166:169], v170 offset:1024
	ds_read_b128 v[176:179], v170 offset:2048
	ds_read_b128 v[180:183], v170 offset:3072
	v_add_u32_e32 v170, s62, v160
	ds_read_b128 v[184:187], v170
	ds_read_b128 v[188:191], v170 offset:1024
	ds_read_b128 v[192:195], v170 offset:2048
	ds_read_b128 v[196:199], v170 offset:3072
	s_add_i32 m0, s37, 0xc000
	ds_read_b128 v[208:211], v161
	ds_read_b128 v[222:225], v161 offset:1024
	ds_read_b128 v[226:229], v161 offset:2048
	ds_read_b128 v[230:233], v161 offset:3072
	ds_read_b128 v[234:237], v161 offset:4096
	ds_read_b128 v[238:241], v161 offset:5120
	ds_read_b128 v[242:245], v161 offset:6144
	ds_read_b128 v[246:249], v161 offset:7168
	global_load_lds_dwordx4 v158, s[14:15]
	s_add_i32 m0, s37, 0xe000
	s_nop 0
	global_load_lds_dwordx4 v156, s[14:15]
	s_waitcnt vmcnt(8)
	s_waitcnt lgkmcnt(0)
	s_barrier
	s_setprio 1
	s_waitcnt lgkmcnt(0)
	v_mfma_f32_16x16x32_bf16 v[126:129], v[162:165], v[208:211], v[126:129]
	v_mfma_f32_16x16x32_bf16 v[118:121], v[176:179], v[208:211], v[118:121]
	v_mfma_f32_16x16x32_bf16 v[110:113], v[162:165], v[226:229], v[110:113]
	v_mfma_f32_16x16x32_bf16 v[102:105], v[176:179], v[226:229], v[102:105]
	v_mfma_f32_16x16x32_bf16 v[94:97], v[162:165], v[234:237], v[94:97]
	v_mfma_f32_16x16x32_bf16 v[86:89], v[176:179], v[234:237], v[86:89]
	v_mfma_f32_16x16x32_bf16 v[78:81], v[162:165], v[242:245], v[78:81]
	v_mfma_f32_16x16x32_bf16 v[70:73], v[176:179], v[242:245], v[70:73]
	v_mfma_f32_16x16x32_bf16 v[126:129], v[166:169], v[222:225], v[126:129]
	v_mfma_f32_16x16x32_bf16 v[118:121], v[180:183], v[222:225], v[118:121]
	v_mfma_f32_16x16x32_bf16 v[110:113], v[166:169], v[230:233], v[110:113]
	v_mfma_f32_16x16x32_bf16 v[102:105], v[180:183], v[230:233], v[102:105]
	v_mfma_f32_16x16x32_bf16 v[94:97], v[166:169], v[238:241], v[94:97]
	v_mfma_f32_16x16x32_bf16 v[86:89], v[180:183], v[238:241], v[86:89]
	v_mfma_f32_16x16x32_bf16 v[78:81], v[166:169], v[246:249], v[78:81]
	v_mfma_f32_16x16x32_bf16 v[70:73], v[180:183], v[246:249], v[70:73]
	s_setprio 0
	s_setprio 1
	v_mfma_f32_16x16x32_bf16 v[122:125], v[184:187], v[208:211], v[122:125]
	v_mfma_f32_16x16x32_bf16 v[114:117], v[192:195], v[208:211], v[114:117]
	v_mfma_f32_16x16x32_bf16 v[106:109], v[184:187], v[226:229], v[106:109]
	v_mfma_f32_16x16x32_bf16 v[98:101], v[192:195], v[226:229], v[98:101]
	v_mfma_f32_16x16x32_bf16 v[90:93], v[184:187], v[234:237], v[90:93]
	v_mfma_f32_16x16x32_bf16 v[82:85], v[192:195], v[234:237], v[82:85]
	v_mfma_f32_16x16x32_bf16 v[74:77], v[184:187], v[242:245], v[74:77]
	v_mfma_f32_16x16x32_bf16 v[66:69], v[192:195], v[242:245], v[66:69]
	v_mfma_f32_16x16x32_bf16 v[122:125], v[188:191], v[222:225], v[122:125]
	v_mfma_f32_16x16x32_bf16 v[114:117], v[196:199], v[222:225], v[114:117]
	v_mfma_f32_16x16x32_bf16 v[106:109], v[188:191], v[230:233], v[106:109]
	v_mfma_f32_16x16x32_bf16 v[98:101], v[196:199], v[230:233], v[98:101]
	v_mfma_f32_16x16x32_bf16 v[90:93], v[188:191], v[238:241], v[90:93]
	v_mfma_f32_16x16x32_bf16 v[82:85], v[196:199], v[238:241], v[82:85]
	v_mfma_f32_16x16x32_bf16 v[74:77], v[188:191], v[246:249], v[74:77]
	v_mfma_f32_16x16x32_bf16 v[66:69], v[196:199], v[246:249], v[66:69]
	s_setprio 0
	s_barrier
	s_add_i32 s60, s60, s36
	s_add_u32 s98, s16, s34
	s_addc_u32 s99, s17, s35
	s_mov_b32 m0, s60
	ds_read_b128 v[208:211], v161 offset:16384
	ds_read_b128 v[222:225], v161 offset:17408
	ds_read_b128 v[226:229], v161 offset:18432
	ds_read_b128 v[230:233], v161 offset:19456
	ds_read_b128 v[234:237], v161 offset:20480
	ds_read_b128 v[238:241], v161 offset:21504
	ds_read_b128 v[242:245], v161 offset:22528
	ds_read_b128 v[246:249], v161 offset:23552
	global_load_lds_dwordx4 v136, s[16:17]
	s_add_i32 m0, s60, 0x2000
	s_add_u32 s60, s16, 0x80000
	s_addc_u32 s61, s17, 0
	s_add_i32 s62, s62, s36
	global_load_lds_dwordx4 v132, s[16:17]
	s_mov_b32 m0, s62
	s_nop 0
	global_load_lds_dwordx4 v136, s[60:61]
	s_add_i32 m0, s62, 0x2000
	s_nop 0
	global_load_lds_dwordx4 v132, s[60:61]
	s_add_u32 s100, s24, s34
	s_addc_u32 s101, s25, s35
	s_mov_b32 m0, s37
	s_nop 0
	global_load_lds_dwordx4 v138, s[24:25]
	s_mov_b32 m0, s38
	s_nop 0
	global_load_lds_dwordx4 v134, s[24:25]
	s_waitcnt vmcnt(8)
	s_waitcnt lgkmcnt(0)
	s_barrier
	s_setprio 1
	s_waitcnt lgkmcnt(0)
	v_mfma_f32_16x16x32_bf16 v[62:65], v[162:165], v[208:211], v[62:65]
	v_mfma_f32_16x16x32_bf16 v[54:57], v[176:179], v[208:211], v[54:57]
	v_mfma_f32_16x16x32_bf16 v[46:49], v[162:165], v[226:229], v[46:49]
	v_mfma_f32_16x16x32_bf16 v[38:41], v[176:179], v[226:229], v[38:41]
	v_mfma_f32_16x16x32_bf16 v[30:33], v[162:165], v[234:237], v[30:33]
	v_mfma_f32_16x16x32_bf16 v[22:25], v[176:179], v[234:237], v[22:25]
	v_mfma_f32_16x16x32_bf16 v[14:17], v[162:165], v[242:245], v[14:17]
	v_mfma_f32_16x16x32_bf16 v[6:9], v[176:179], v[242:245], v[6:9]
	v_mfma_f32_16x16x32_bf16 v[62:65], v[166:169], v[222:225], v[62:65]
	v_mfma_f32_16x16x32_bf16 v[54:57], v[180:183], v[222:225], v[54:57]
	v_mfma_f32_16x16x32_bf16 v[46:49], v[166:169], v[230:233], v[46:49]
	v_mfma_f32_16x16x32_bf16 v[38:41], v[180:183], v[230:233], v[38:41]
	v_mfma_f32_16x16x32_bf16 v[30:33], v[166:169], v[238:241], v[30:33]
	v_mfma_f32_16x16x32_bf16 v[22:25], v[180:183], v[238:241], v[22:25]
	v_mfma_f32_16x16x32_bf16 v[14:17], v[166:169], v[246:249], v[14:17]
	v_mfma_f32_16x16x32_bf16 v[6:9], v[180:183], v[246:249], v[6:9]
	s_setprio 0
	s_setprio 1
	v_mfma_f32_16x16x32_bf16 v[58:61], v[184:187], v[208:211], v[58:61]
	v_mfma_f32_16x16x32_bf16 v[50:53], v[192:195], v[208:211], v[50:53]
	v_mfma_f32_16x16x32_bf16 v[42:45], v[184:187], v[226:229], v[42:45]
	v_mfma_f32_16x16x32_bf16 v[34:37], v[192:195], v[226:229], v[34:37]
	v_mfma_f32_16x16x32_bf16 v[26:29], v[184:187], v[234:237], v[26:29]
	v_mfma_f32_16x16x32_bf16 v[18:21], v[192:195], v[234:237], v[18:21]
	v_mfma_f32_16x16x32_bf16 v[10:13], v[184:187], v[242:245], v[10:13]
	v_mfma_f32_16x16x32_bf16 v[2:5], v[192:195], v[242:245], v[2:5]
	v_mfma_f32_16x16x32_bf16 v[58:61], v[188:191], v[222:225], v[58:61]
	v_mfma_f32_16x16x32_bf16 v[50:53], v[196:199], v[222:225], v[50:53]
	v_mfma_f32_16x16x32_bf16 v[42:45], v[188:191], v[230:233], v[42:45]
	v_mfma_f32_16x16x32_bf16 v[34:37], v[196:199], v[230:233], v[34:37]
	v_mfma_f32_16x16x32_bf16 v[26:29], v[188:191], v[238:241], v[26:29]
	v_mfma_f32_16x16x32_bf16 v[18:21], v[196:199], v[238:241], v[18:21]
	v_mfma_f32_16x16x32_bf16 v[10:13], v[188:191], v[246:249], v[10:13]
	v_mfma_f32_16x16x32_bf16 v[2:5], v[196:199], v[246:249], v[2:5]
	s_setprio 0
	s_barrier
	s_add_i32 s60, 0, 0x18000
	v_add_u32_e32 v172, s60, v160
	s_add_i32 s61, 0, 0x1c000
	ds_read_b128 v[162:165], v172
	ds_read_b128 v[166:169], v172 offset:1024
	ds_read_b128 v[176:179], v172 offset:2048
	ds_read_b128 v[180:183], v172 offset:3072
	v_add_u32_e32 v172, s61, v160
	ds_read_b128 v[184:187], v172
	ds_read_b128 v[188:191], v172 offset:1024
	ds_read_b128 v[192:195], v172 offset:2048
	ds_read_b128 v[196:199], v172 offset:3072
	s_add_u32 s24, s24, 0x80000
	s_addc_u32 s25, s25, 0
	s_mov_b32 m0, s39
	ds_read_b128 v[208:211], v161 offset:32768
	ds_read_b128 v[222:225], v161 offset:33792
	ds_read_b128 v[226:229], v161 offset:34816
	ds_read_b128 v[230:233], v161 offset:35840
	ds_read_b128 v[234:237], v161 offset:36864
	ds_read_b128 v[238:241], v161 offset:37888
	ds_read_b128 v[242:245], v161 offset:38912
	ds_read_b128 v[246:249], v161 offset:39936
	global_load_lds_dwordx4 v138, s[24:25]
	s_mov_b32 m0, s40
	s_nop 0
	global_load_lds_dwordx4 v134, s[24:25]
	s_waitcnt vmcnt(8)
	s_waitcnt lgkmcnt(0)
	s_barrier
	s_setprio 1
	s_waitcnt lgkmcnt(0)
	v_mfma_f32_16x16x32_bf16 v[126:129], v[162:165], v[208:211], v[126:129]
	v_mfma_f32_16x16x32_bf16 v[118:121], v[176:179], v[208:211], v[118:121]
	v_mfma_f32_16x16x32_bf16 v[110:113], v[162:165], v[226:229], v[110:113]
	v_mfma_f32_16x16x32_bf16 v[102:105], v[176:179], v[226:229], v[102:105]
	v_mfma_f32_16x16x32_bf16 v[94:97], v[162:165], v[234:237], v[94:97]
	v_mfma_f32_16x16x32_bf16 v[86:89], v[176:179], v[234:237], v[86:89]
	v_mfma_f32_16x16x32_bf16 v[78:81], v[162:165], v[242:245], v[78:81]
	v_mfma_f32_16x16x32_bf16 v[70:73], v[176:179], v[242:245], v[70:73]
	v_mfma_f32_16x16x32_bf16 v[126:129], v[166:169], v[222:225], v[126:129]
	v_mfma_f32_16x16x32_bf16 v[118:121], v[180:183], v[222:225], v[118:121]
	v_mfma_f32_16x16x32_bf16 v[110:113], v[166:169], v[230:233], v[110:113]
	v_mfma_f32_16x16x32_bf16 v[102:105], v[180:183], v[230:233], v[102:105]
	v_mfma_f32_16x16x32_bf16 v[94:97], v[166:169], v[238:241], v[94:97]
	v_mfma_f32_16x16x32_bf16 v[86:89], v[180:183], v[238:241], v[86:89]
	v_mfma_f32_16x16x32_bf16 v[78:81], v[166:169], v[246:249], v[78:81]
	v_mfma_f32_16x16x32_bf16 v[70:73], v[180:183], v[246:249], v[70:73]
	s_setprio 0
	s_setprio 1
	v_mfma_f32_16x16x32_bf16 v[122:125], v[184:187], v[208:211], v[122:125]
	v_mfma_f32_16x16x32_bf16 v[114:117], v[192:195], v[208:211], v[114:117]
	v_mfma_f32_16x16x32_bf16 v[106:109], v[184:187], v[226:229], v[106:109]
	v_mfma_f32_16x16x32_bf16 v[98:101], v[192:195], v[226:229], v[98:101]
	v_mfma_f32_16x16x32_bf16 v[90:93], v[184:187], v[234:237], v[90:93]
	v_mfma_f32_16x16x32_bf16 v[82:85], v[192:195], v[234:237], v[82:85]
	v_mfma_f32_16x16x32_bf16 v[74:77], v[184:187], v[242:245], v[74:77]
	v_mfma_f32_16x16x32_bf16 v[66:69], v[192:195], v[242:245], v[66:69]
	v_mfma_f32_16x16x32_bf16 v[122:125], v[188:191], v[222:225], v[122:125]
	v_mfma_f32_16x16x32_bf16 v[114:117], v[196:199], v[222:225], v[114:117]
	v_mfma_f32_16x16x32_bf16 v[106:109], v[188:191], v[230:233], v[106:109]
	v_mfma_f32_16x16x32_bf16 v[98:101], v[196:199], v[230:233], v[98:101]
	v_mfma_f32_16x16x32_bf16 v[90:93], v[188:191], v[238:241], v[90:93]
	v_mfma_f32_16x16x32_bf16 v[82:85], v[196:199], v[238:241], v[82:85]
	v_mfma_f32_16x16x32_bf16 v[74:77], v[188:191], v[246:249], v[74:77]
	v_mfma_f32_16x16x32_bf16 v[66:69], v[196:199], v[246:249], v[66:69]
	s_setprio 0
	s_barrier
	s_add_i32 s24, s60, s36
	s_mov_b32 m0, s24
	ds_read_b128 v[208:211], v161 offset:49152
	ds_read_b128 v[222:225], v161 offset:50176
	ds_read_b128 v[226:229], v161 offset:51200
	ds_read_b128 v[230:233], v161 offset:52224
	ds_read_b128 v[234:237], v161 offset:53248
	ds_read_b128 v[238:241], v161 offset:54272
	ds_read_b128 v[242:245], v161 offset:55296
	ds_read_b128 v[246:249], v161 offset:56320
	global_load_lds_dwordx4 v136, s[98:99]
	s_add_i32 m0, s24, 0x2000
	s_add_u32 s16, s16, 0x80080
	s_addc_u32 s17, s17, 0
	s_add_i32 s24, s61, s36
	global_load_lds_dwordx4 v132, s[98:99]
	s_mov_b32 m0, s24
	s_nop 0
	global_load_lds_dwordx4 v136, s[16:17]
	s_add_i32 m0, s24, 0x2000
	s_nop 0
	global_load_lds_dwordx4 v132, s[16:17]
	s_mov_b32 m0, s45
	s_nop 0
	global_load_lds_dwordx4 v138, s[100:101]
	s_mov_b32 m0, s46
	s_nop 0
	global_load_lds_dwordx4 v134, s[100:101]
	s_waitcnt vmcnt(8)
	s_waitcnt lgkmcnt(0)
	s_barrier
	s_setprio 1
	s_waitcnt lgkmcnt(0)
	v_mfma_f32_16x16x32_bf16 v[62:65], v[162:165], v[208:211], v[62:65]
	v_mfma_f32_16x16x32_bf16 v[54:57], v[176:179], v[208:211], v[54:57]
	v_mfma_f32_16x16x32_bf16 v[46:49], v[162:165], v[226:229], v[46:49]
	v_mfma_f32_16x16x32_bf16 v[38:41], v[176:179], v[226:229], v[38:41]
	v_mfma_f32_16x16x32_bf16 v[30:33], v[162:165], v[234:237], v[30:33]
	v_mfma_f32_16x16x32_bf16 v[22:25], v[176:179], v[234:237], v[22:25]
	v_mfma_f32_16x16x32_bf16 v[14:17], v[162:165], v[242:245], v[14:17]
	v_mfma_f32_16x16x32_bf16 v[6:9], v[176:179], v[242:245], v[6:9]
	v_mfma_f32_16x16x32_bf16 v[62:65], v[166:169], v[222:225], v[62:65]
	v_mfma_f32_16x16x32_bf16 v[54:57], v[180:183], v[222:225], v[54:57]
	v_mfma_f32_16x16x32_bf16 v[46:49], v[166:169], v[230:233], v[46:49]
	v_mfma_f32_16x16x32_bf16 v[38:41], v[180:183], v[230:233], v[38:41]
	v_mfma_f32_16x16x32_bf16 v[30:33], v[166:169], v[238:241], v[30:33]
	v_mfma_f32_16x16x32_bf16 v[22:25], v[180:183], v[238:241], v[22:25]
	v_mfma_f32_16x16x32_bf16 v[14:17], v[166:169], v[246:249], v[14:17]
	v_mfma_f32_16x16x32_bf16 v[6:9], v[180:183], v[246:249], v[6:9]
	s_setprio 0
	s_setprio 1
	v_mfma_f32_16x16x32_bf16 v[58:61], v[184:187], v[208:211], v[58:61]
	v_mfma_f32_16x16x32_bf16 v[50:53], v[192:195], v[208:211], v[50:53]
	v_mfma_f32_16x16x32_bf16 v[42:45], v[184:187], v[226:229], v[42:45]
	v_mfma_f32_16x16x32_bf16 v[34:37], v[192:195], v[226:229], v[34:37]
	v_mfma_f32_16x16x32_bf16 v[26:29], v[184:187], v[234:237], v[26:29]
	v_mfma_f32_16x16x32_bf16 v[18:21], v[192:195], v[234:237], v[18:21]
	v_mfma_f32_16x16x32_bf16 v[10:13], v[184:187], v[242:245], v[10:13]
	v_mfma_f32_16x16x32_bf16 v[2:5], v[192:195], v[242:245], v[2:5]
	v_mfma_f32_16x16x32_bf16 v[58:61], v[188:191], v[222:225], v[58:61]
	v_mfma_f32_16x16x32_bf16 v[50:53], v[196:199], v[222:225], v[50:53]
	v_mfma_f32_16x16x32_bf16 v[42:45], v[188:191], v[230:233], v[42:45]
	v_mfma_f32_16x16x32_bf16 v[34:37], v[196:199], v[230:233], v[34:37]
	v_mfma_f32_16x16x32_bf16 v[26:29], v[188:191], v[238:241], v[26:29]
	v_mfma_f32_16x16x32_bf16 v[18:21], v[196:199], v[238:241], v[18:21]
	v_mfma_f32_16x16x32_bf16 v[10:13], v[188:191], v[246:249], v[10:13]
	v_mfma_f32_16x16x32_bf16 v[2:5], v[196:199], v[246:249], v[2:5]
	s_setprio 0
	s_barrier
	s_add_i32 s59, s59, 2
	s_add_u32 s57, s57, 0x100
	s_addc_u32 s58, s58, 0
	s_add_u32 s14, s14, 0x100
	s_addc_u32 s15, s15, 0
	s_cmp_gt_u32 s59, 29
	s_cbranch_scc0 .LBB0_1188
	s_and_b64 vcc, exec, s[4:5]
	s_cbranch_vccz .LBB0_1191
	s_barrier

.LBB0_1276:
	s_add_i32 vcc_lo, s38, 2
	s_add_u32 s10, s30, 0x4000
	s_addc_u32 s11, s31, 0
	s_cmp_eq_u32 s5, s38
	s_cselect_b32 s42, s16, s10
	s_cselect_b32 s43, s17, s11
	s_cselect_b32 s40, s28, s44
	s_cselect_b32 s41, s29, s45
	s_add_u32 s38, s42, 0x8000
	s_addc_u32 s39, s43, 0
	s_add_i32 s10, 0, 0x10000
	v_add_u32_e32 v130, s10, v210
	s_add_i32 vcc_hi, 0, 0x14000
	ds_read_b128 v[132:135], v130
	ds_read_b128 v[136:139], v130 offset:1024
	ds_read_b128 v[140:143], v130 offset:2048
	ds_read_b128 v[144:147], v130 offset:3072
	v_add_u32_e32 v130, vcc_hi, v210
	ds_read_b128 v[148:151], v130
	ds_read_b128 v[152:155], v130 offset:1024
	ds_read_b128 v[156:159], v130 offset:2048
	ds_read_b128 v[160:163], v130 offset:3072
	s_add_i32 m0, s62, 0xc000
	ds_read_b128 v[164:167], v212
	ds_read_b128 v[168:171], v212 offset:1024
	ds_read_b128 v[188:191], v212 offset:2048
	ds_read_b128 v[192:195], v212 offset:3072
	ds_read_b128 v[196:199], v212 offset:4096
	ds_read_b128 v[222:225], v212 offset:5120
	ds_read_b128 v[226:229], v212 offset:6144
	ds_read_b128 v[230:233], v212 offset:7168
	global_load_lds_dwordx4 v186, s[30:31]
	s_add_i32 m0, s62, 0xe000
	s_nop 0
	global_load_lds_dwordx4 v184, s[30:31]
	s_waitcnt vmcnt(8)
	s_waitcnt lgkmcnt(0)
	s_barrier
	s_setprio 1
	s_waitcnt lgkmcnt(0)
	v_mfma_f32_16x16x32_bf16 v[2:5], v[132:135], v[164:167], v[2:5]
	v_mfma_f32_16x16x32_bf16 v[6:9], v[140:143], v[164:167], v[6:9]
	v_mfma_f32_16x16x32_bf16 v[10:13], v[132:135], v[188:191], v[10:13]
	v_mfma_f32_16x16x32_bf16 v[14:17], v[140:143], v[188:191], v[14:17]
	v_mfma_f32_16x16x32_bf16 v[18:21], v[132:135], v[196:199], v[18:21]
	v_mfma_f32_16x16x32_bf16 v[22:25], v[140:143], v[196:199], v[22:25]
	v_mfma_f32_16x16x32_bf16 v[26:29], v[132:135], v[226:229], v[26:29]
	v_mfma_f32_16x16x32_bf16 v[30:33], v[140:143], v[226:229], v[30:33]
	v_mfma_f32_16x16x32_bf16 v[2:5], v[136:139], v[168:171], v[2:5]
	v_mfma_f32_16x16x32_bf16 v[6:9], v[144:147], v[168:171], v[6:9]
	v_mfma_f32_16x16x32_bf16 v[10:13], v[136:139], v[192:195], v[10:13]
	v_mfma_f32_16x16x32_bf16 v[14:17], v[144:147], v[192:195], v[14:17]
	v_mfma_f32_16x16x32_bf16 v[18:21], v[136:139], v[222:225], v[18:21]
	v_mfma_f32_16x16x32_bf16 v[22:25], v[144:147], v[222:225], v[22:25]
	v_mfma_f32_16x16x32_bf16 v[26:29], v[136:139], v[230:233], v[26:29]
	v_mfma_f32_16x16x32_bf16 v[30:33], v[144:147], v[230:233], v[30:33]
	s_setprio 0
	s_setprio 1
	v_mfma_f32_16x16x32_bf16 v[34:37], v[148:151], v[164:167], v[34:37]
	v_mfma_f32_16x16x32_bf16 v[38:41], v[156:159], v[164:167], v[38:41]
	v_mfma_f32_16x16x32_bf16 v[42:45], v[148:151], v[188:191], v[42:45]
	v_mfma_f32_16x16x32_bf16 v[46:49], v[156:159], v[188:191], v[46:49]
	v_mfma_f32_16x16x32_bf16 v[50:53], v[148:151], v[196:199], v[50:53]
	v_mfma_f32_16x16x32_bf16 v[54:57], v[156:159], v[196:199], v[54:57]
	v_mfma_f32_16x16x32_bf16 v[58:61], v[148:151], v[226:229], v[58:61]
	v_mfma_f32_16x16x32_bf16 v[62:65], v[156:159], v[226:229], v[62:65]
	v_mfma_f32_16x16x32_bf16 v[34:37], v[152:155], v[168:171], v[34:37]
	v_mfma_f32_16x16x32_bf16 v[38:41], v[160:163], v[168:171], v[38:41]
	v_mfma_f32_16x16x32_bf16 v[42:45], v[152:155], v[192:195], v[42:45]
	v_mfma_f32_16x16x32_bf16 v[46:49], v[160:163], v[192:195], v[46:49]
	v_mfma_f32_16x16x32_bf16 v[50:53], v[152:155], v[222:225], v[50:53]
	v_mfma_f32_16x16x32_bf16 v[54:57], v[160:163], v[222:225], v[54:57]
	v_mfma_f32_16x16x32_bf16 v[58:61], v[152:155], v[230:233], v[58:61]
	v_mfma_f32_16x16x32_bf16 v[62:65], v[160:163], v[230:233], v[62:65]
	s_setprio 0
	s_barrier
	s_add_i32 s10, s10, s61
	s_add_u32 s98, s40, s34
	s_addc_u32 s99, s41, s35
	s_mov_b32 m0, s10
	ds_read_b128 v[164:167], v212 offset:16384
	ds_read_b128 v[168:171], v212 offset:17408
	ds_read_b128 v[188:191], v212 offset:18432
	ds_read_b128 v[192:195], v212 offset:19456
	ds_read_b128 v[196:199], v212 offset:20480
	ds_read_b128 v[222:225], v212 offset:21504
	ds_read_b128 v[226:229], v212 offset:22528
	ds_read_b128 v[230:233], v212 offset:23552
	global_load_lds_dwordx4 v178, s[40:41]
	s_add_i32 m0, s10, 0x2000
	s_add_u32 s10, s40, 0x160000
	s_addc_u32 s11, s41, 0
	s_add_i32 vcc_hi, vcc_hi, s61
	global_load_lds_dwordx4 v182, s[40:41]
	s_mov_b32 m0, vcc_hi
	s_nop 0
	global_load_lds_dwordx4 v178, s[10:11]
	s_add_i32 m0, vcc_hi, 0x2000
	s_nop 0
	global_load_lds_dwordx4 v182, s[10:11]
	s_mov_b32 m0, s62
	s_nop 0
	global_load_lds_dwordx4 v176, s[42:43]
	s_mov_b32 m0, s63
	s_nop 0
	global_load_lds_dwordx4 v180, s[42:43]
	s_waitcnt vmcnt(8)
	s_waitcnt lgkmcnt(0)
	s_barrier
	s_setprio 1
	s_waitcnt lgkmcnt(0)
	v_mfma_f32_16x16x32_bf16 v[66:69], v[132:135], v[164:167], v[66:69]
	v_mfma_f32_16x16x32_bf16 v[70:73], v[140:143], v[164:167], v[70:73]
	v_mfma_f32_16x16x32_bf16 v[74:77], v[132:135], v[188:191], v[74:77]
	v_mfma_f32_16x16x32_bf16 v[78:81], v[140:143], v[188:191], v[78:81]
	v_mfma_f32_16x16x32_bf16 v[82:85], v[132:135], v[196:199], v[82:85]
	v_mfma_f32_16x16x32_bf16 v[86:89], v[140:143], v[196:199], v[86:89]
	v_mfma_f32_16x16x32_bf16 v[90:93], v[132:135], v[226:229], v[90:93]
	v_mfma_f32_16x16x32_bf16 v[94:97], v[140:143], v[226:229], v[94:97]
	v_mfma_f32_16x16x32_bf16 v[66:69], v[136:139], v[168:171], v[66:69]
	v_mfma_f32_16x16x32_bf16 v[70:73], v[144:147], v[168:171], v[70:73]
	v_mfma_f32_16x16x32_bf16 v[74:77], v[136:139], v[192:195], v[74:77]
	v_mfma_f32_16x16x32_bf16 v[78:81], v[144:147], v[192:195], v[78:81]
	v_mfma_f32_16x16x32_bf16 v[82:85], v[136:139], v[222:225], v[82:85]
	v_mfma_f32_16x16x32_bf16 v[86:89], v[144:147], v[222:225], v[86:89]
	v_mfma_f32_16x16x32_bf16 v[90:93], v[136:139], v[230:233], v[90:93]
	v_mfma_f32_16x16x32_bf16 v[94:97], v[144:147], v[230:233], v[94:97]
	s_setprio 0
	s_setprio 1
	v_mfma_f32_16x16x32_bf16 v[98:101], v[148:151], v[164:167], v[98:101]
	v_mfma_f32_16x16x32_bf16 v[102:105], v[156:159], v[164:167], v[102:105]
	v_mfma_f32_16x16x32_bf16 v[106:109], v[148:151], v[188:191], v[106:109]
	v_mfma_f32_16x16x32_bf16 v[110:113], v[156:159], v[188:191], v[110:113]
	v_mfma_f32_16x16x32_bf16 v[114:117], v[148:151], v[196:199], v[114:117]
	v_mfma_f32_16x16x32_bf16 v[118:121], v[156:159], v[196:199], v[118:121]
	v_mfma_f32_16x16x32_bf16 v[122:125], v[148:151], v[226:229], v[122:125]
	v_mfma_f32_16x16x32_bf16 v[126:129], v[156:159], v[226:229], v[126:129]
	v_mfma_f32_16x16x32_bf16 v[98:101], v[152:155], v[168:171], v[98:101]
	v_mfma_f32_16x16x32_bf16 v[102:105], v[160:163], v[168:171], v[102:105]
	v_mfma_f32_16x16x32_bf16 v[106:109], v[152:155], v[192:195], v[106:109]
	v_mfma_f32_16x16x32_bf16 v[110:113], v[160:163], v[192:195], v[110:113]
	v_mfma_f32_16x16x32_bf16 v[114:117], v[152:155], v[222:225], v[114:117]
	v_mfma_f32_16x16x32_bf16 v[118:121], v[160:163], v[222:225], v[118:121]
	v_mfma_f32_16x16x32_bf16 v[122:125], v[152:155], v[230:233], v[122:125]
	v_mfma_f32_16x16x32_bf16 v[126:129], v[160:163], v[230:233], v[126:129]
	s_setprio 0
	s_barrier
	s_add_i32 vcc_hi, 0, 0x18000
	v_add_u32_e32 v130, vcc_hi, v210
	s_add_i32 s81, 0, 0x1c000
	ds_read_b128 v[132:135], v130
	ds_read_b128 v[136:139], v130 offset:1024
	ds_read_b128 v[140:143], v130 offset:2048
	ds_read_b128 v[144:147], v130 offset:3072
	v_add_u32_e32 v130, s81, v210
	ds_read_b128 v[148:151], v130
	ds_read_b128 v[152:155], v130 offset:1024
	ds_read_b128 v[156:159], v130 offset:2048
	ds_read_b128 v[160:163], v130 offset:3072
	s_add_u32 s10, s42, 0x4000
	s_addc_u32 s11, s43, 0
	s_mov_b32 m0, s68
	ds_read_b128 v[164:167], v212 offset:32768
	ds_read_b128 v[168:171], v212 offset:33792
	ds_read_b128 v[188:191], v212 offset:34816
	ds_read_b128 v[192:195], v212 offset:35840
	ds_read_b128 v[196:199], v212 offset:36864
	ds_read_b128 v[222:225], v212 offset:37888
	ds_read_b128 v[226:229], v212 offset:38912
	ds_read_b128 v[230:233], v212 offset:39936
	global_load_lds_dwordx4 v176, s[10:11]
	s_mov_b32 m0, s69
	s_nop 0
	global_load_lds_dwordx4 v180, s[10:11]
	s_waitcnt vmcnt(8)
	s_waitcnt lgkmcnt(0)
	s_barrier
	s_setprio 1
	s_waitcnt lgkmcnt(0)
	v_mfma_f32_16x16x32_bf16 v[2:5], v[132:135], v[164:167], v[2:5]
	v_mfma_f32_16x16x32_bf16 v[6:9], v[140:143], v[164:167], v[6:9]
	v_mfma_f32_16x16x32_bf16 v[10:13], v[132:135], v[188:191], v[10:13]
	v_mfma_f32_16x16x32_bf16 v[14:17], v[140:143], v[188:191], v[14:17]
	v_mfma_f32_16x16x32_bf16 v[18:21], v[132:135], v[196:199], v[18:21]
	v_mfma_f32_16x16x32_bf16 v[22:25], v[140:143], v[196:199], v[22:25]
	v_mfma_f32_16x16x32_bf16 v[26:29], v[132:135], v[226:229], v[26:29]
	v_mfma_f32_16x16x32_bf16 v[30:33], v[140:143], v[226:229], v[30:33]
	v_mfma_f32_16x16x32_bf16 v[2:5], v[136:139], v[168:171], v[2:5]
	v_mfma_f32_16x16x32_bf16 v[6:9], v[144:147], v[168:171], v[6:9]
	v_mfma_f32_16x16x32_bf16 v[10:13], v[136:139], v[192:195], v[10:13]
	v_mfma_f32_16x16x32_bf16 v[14:17], v[144:147], v[192:195], v[14:17]
	v_mfma_f32_16x16x32_bf16 v[18:21], v[136:139], v[222:225], v[18:21]
	v_mfma_f32_16x16x32_bf16 v[22:25], v[144:147], v[222:225], v[22:25]
	v_mfma_f32_16x16x32_bf16 v[26:29], v[136:139], v[230:233], v[26:29]
	v_mfma_f32_16x16x32_bf16 v[30:33], v[144:147], v[230:233], v[30:33]
	s_setprio 0
	s_setprio 1
	v_mfma_f32_16x16x32_bf16 v[34:37], v[148:151], v[164:167], v[34:37]
	v_mfma_f32_16x16x32_bf16 v[38:41], v[156:159], v[164:167], v[38:41]
	v_mfma_f32_16x16x32_bf16 v[42:45], v[148:151], v[188:191], v[42:45]
	v_mfma_f32_16x16x32_bf16 v[46:49], v[156:159], v[188:191], v[46:49]
	v_mfma_f32_16x16x32_bf16 v[50:53], v[148:151], v[196:199], v[50:53]
	v_mfma_f32_16x16x32_bf16 v[54:57], v[156:159], v[196:199], v[54:57]
	v_mfma_f32_16x16x32_bf16 v[58:61], v[148:151], v[226:229], v[58:61]
	v_mfma_f32_16x16x32_bf16 v[62:65], v[156:159], v[226:229], v[62:65]
	v_mfma_f32_16x16x32_bf16 v[34:37], v[152:155], v[168:171], v[34:37]
	v_mfma_f32_16x16x32_bf16 v[38:41], v[160:163], v[168:171], v[38:41]
	v_mfma_f32_16x16x32_bf16 v[42:45], v[152:155], v[192:195], v[42:45]
	v_mfma_f32_16x16x32_bf16 v[46:49], v[160:163], v[192:195], v[46:49]
	v_mfma_f32_16x16x32_bf16 v[50:53], v[152:155], v[222:225], v[50:53]
	v_mfma_f32_16x16x32_bf16 v[54:57], v[160:163], v[222:225], v[54:57]
	v_mfma_f32_16x16x32_bf16 v[58:61], v[152:155], v[230:233], v[58:61]
	v_mfma_f32_16x16x32_bf16 v[62:65], v[160:163], v[230:233], v[62:65]
	s_setprio 0
	s_barrier
	s_add_i32 s10, vcc_hi, s61
	s_mov_b32 m0, s10
	ds_read_b128 v[164:167], v212 offset:49152
	ds_read_b128 v[168:171], v212 offset:50176
	ds_read_b128 v[188:191], v212 offset:51200
	ds_read_b128 v[192:195], v212 offset:52224
	ds_read_b128 v[196:199], v212 offset:53248
	ds_read_b128 v[222:225], v212 offset:54272
	ds_read_b128 v[226:229], v212 offset:55296
	ds_read_b128 v[230:233], v212 offset:56320
	global_load_lds_dwordx4 v178, s[98:99]
	s_add_i32 m0, s10, 0x2000
	s_add_u32 s10, s40, 0x160080
	s_addc_u32 s11, s41, 0
	s_add_i32 s40, s81, s61
	global_load_lds_dwordx4 v182, s[98:99]
	s_mov_b32 m0, s40
	s_nop 0
	global_load_lds_dwordx4 v178, s[10:11]
	s_add_i32 m0, s40, 0x2000
	s_nop 0
	global_load_lds_dwordx4 v182, s[10:11]
	s_mov_b32 m0, s75
	s_nop 0
	global_load_lds_dwordx4 v176, s[38:39]
	s_mov_b32 m0, s76
	s_nop 0
	global_load_lds_dwordx4 v180, s[38:39]
	s_waitcnt vmcnt(8)
	s_waitcnt lgkmcnt(0)
	s_barrier
	s_setprio 1
	s_waitcnt lgkmcnt(0)
	v_mfma_f32_16x16x32_bf16 v[66:69], v[132:135], v[164:167], v[66:69]
	v_mfma_f32_16x16x32_bf16 v[70:73], v[140:143], v[164:167], v[70:73]
	v_mfma_f32_16x16x32_bf16 v[74:77], v[132:135], v[188:191], v[74:77]
	v_mfma_f32_16x16x32_bf16 v[78:81], v[140:143], v[188:191], v[78:81]
	v_mfma_f32_16x16x32_bf16 v[82:85], v[132:135], v[196:199], v[82:85]
	v_mfma_f32_16x16x32_bf16 v[86:89], v[140:143], v[196:199], v[86:89]
	v_mfma_f32_16x16x32_bf16 v[90:93], v[132:135], v[226:229], v[90:93]
	v_mfma_f32_16x16x32_bf16 v[94:97], v[140:143], v[226:229], v[94:97]
	v_mfma_f32_16x16x32_bf16 v[66:69], v[136:139], v[168:171], v[66:69]
	v_mfma_f32_16x16x32_bf16 v[70:73], v[144:147], v[168:171], v[70:73]
	v_mfma_f32_16x16x32_bf16 v[74:77], v[136:139], v[192:195], v[74:77]
	v_mfma_f32_16x16x32_bf16 v[78:81], v[144:147], v[192:195], v[78:81]
	v_mfma_f32_16x16x32_bf16 v[82:85], v[136:139], v[222:225], v[82:85]
	v_mfma_f32_16x16x32_bf16 v[86:89], v[144:147], v[222:225], v[86:89]
	v_mfma_f32_16x16x32_bf16 v[90:93], v[136:139], v[230:233], v[90:93]
	v_mfma_f32_16x16x32_bf16 v[94:97], v[144:147], v[230:233], v[94:97]
	s_setprio 0
	s_setprio 1
	v_mfma_f32_16x16x32_bf16 v[98:101], v[148:151], v[164:167], v[98:101]
	v_mfma_f32_16x16x32_bf16 v[102:105], v[156:159], v[164:167], v[102:105]
	v_mfma_f32_16x16x32_bf16 v[106:109], v[148:151], v[188:191], v[106:109]
	v_mfma_f32_16x16x32_bf16 v[110:113], v[156:159], v[188:191], v[110:113]
	v_mfma_f32_16x16x32_bf16 v[114:117], v[148:151], v[196:199], v[114:117]
	v_mfma_f32_16x16x32_bf16 v[118:121], v[156:159], v[196:199], v[118:121]
	v_mfma_f32_16x16x32_bf16 v[122:125], v[148:151], v[226:229], v[122:125]
	v_mfma_f32_16x16x32_bf16 v[126:129], v[156:159], v[226:229], v[126:129]
	v_mfma_f32_16x16x32_bf16 v[98:101], v[152:155], v[168:171], v[98:101]
	v_mfma_f32_16x16x32_bf16 v[102:105], v[160:163], v[168:171], v[102:105]
	v_mfma_f32_16x16x32_bf16 v[106:109], v[152:155], v[192:195], v[106:109]
	v_mfma_f32_16x16x32_bf16 v[110:113], v[160:163], v[192:195], v[110:113]
	v_mfma_f32_16x16x32_bf16 v[114:117], v[152:155], v[222:225], v[114:117]
	v_mfma_f32_16x16x32_bf16 v[118:121], v[160:163], v[222:225], v[118:121]
	v_mfma_f32_16x16x32_bf16 v[122:125], v[152:155], v[230:233], v[122:125]
	v_mfma_f32_16x16x32_bf16 v[126:129], v[160:163], v[230:233], v[126:129]
	s_setprio 0
	s_barrier
	s_add_u32 s44, s44, 0x100
	s_addc_u32 s45, s45, 0
	s_add_u32 s30, s30, 0x10000
	s_addc_u32 s31, s31, 0
	s_cmp_ge_i32 vcc_lo, s54
	s_mov_b32 s38, vcc_lo
	s_cbranch_scc0 .LBB0_1276
